# baseline (speedup 1.0000x reference)
; #define PG8_STAGE(bufoff, gbase, voff) do { _Pragma("unroll") for (int _i = 0; _i < 2; ++_i) \
;         __builtin_amdgcn_global_load_lds((const unsigned*)((const char*)(gbase) + (voff)[_i]), (LAS unsigned*)(lds + (bufoff) + ldsw + _i * 8192), 16, 0, 0); } while (0)
; #define PG8_LDA(dst, b, h) do { _Pragma("unroll") for (int m = 0; m < 4; ++m) _Pragma("unroll") for (int k = 0; k < 2; ++k) dst[m][k] = *(const LAS bf16x8*)(lds + PG8_SA(b, h) + aoff + m * 2048 + k * 1024); } while (0)
; #define PG8_LDB(dst, b, h) do { _Pragma("unroll") for (int n = 0; n < 2; ++n) _Pragma("unroll") for (int k = 0; k < 2; ++k) dst[n][k] = *(const LAS bf16x8*)(lds + PG8_SB(b, h) + boff + n * 2048 + k * 1024); } while (0)
; #define PG8_MMA(ai, bj, At, Bt) do { __builtin_amdgcn_s_setprio(1); _Pragma("unroll") for (int m = 0; m < 4; ++m) _Pragma("unroll") for (int n = 0; n < 2; ++n) _Pragma("unroll") for (int k = 0; k < 2; ++k) \
;         acc[ai][bj][m][n] = __builtin_amdgcn_mfma_f32_16x16x32_bf16(Bt[n][k], At[m][k], acc[ai][bj][m][n], 0, 0, 0); __builtin_amdgcn_s_setprio(0); } while (0)
; #define PG8_WAIT_L(n) asm volatile("s_waitcnt lgkmcnt(" #n ")" ::: "memory")
; #define PG8_BAR __builtin_amdgcn_s_barrier()
; #define PG8_SCHED __builtin_amdgcn_sched_barrier(0)
; template <class Epi>
; DEV void gemm_phase(LAS unsigned char* lds, const Gemm g, const StaticOrder& S, const Epi& E) {
;     ...
;             PG8_LDB(B0, 0, 0); PG8_SCHED; PG8_LDA(At, 0, 0); PG8_STAGE(PG8_SA(1, 1), a1 + hstep, voffA);
;             PG8_WAIT_L(8); PG8_BAR; PG8_WAIT_L(0); PG8_MMA(0, 0, At, B0); PG8_BAR; PG8_SCHED;
;             PG8_LDB(B1, 0, 1); PG8_STAGE(PG8_SB(0, 0), b2, voffB);
;             PG8_BAR; PG8_WAIT_L(0); PG8_MMA(0, 1, At, B1); PG8_BAR;
;             PG8_LDA(At, 0, 1); PG8_STAGE(PG8_SA(0, 0), a2, voffA);
;             PG8_BAR; PG8_WAIT_L(0); PG8_MMA(1, 0, At, B0); PG8_BAR; PG8_SCHED;
.LBB0_152:
	s_add_u32 s20, s18, 0xfff80080
	s_addc_u32 s21, s19, -1
	s_add_i32 s41, 0, 0x10000
	v_add_u32_e32 v140, s41, v176
	ds_read_b128 v[128:131], v140
	ds_read_b128 v[132:135], v140 offset:1024
	ds_read_b128 v[136:139], v140 offset:2048
	ds_read_b128 v[140:143], v140 offset:3072
	s_cmp_eq_u32 s40, 28
	s_cselect_b32 s23, s5, s21
	s_cselect_b32 s22, s11, s20
	s_cselect_b32 s21, s9, s39
	s_cselect_b32 s20, s37, s38
	v_lshl_add_u64 v[158:159], s[18:19], 0, v[154:155]
	s_add_i32 m0, s17, 0xc000
	ds_read_b128 v[180:183], v178
	ds_read_b128 v[184:187], v178 offset:1024
	ds_read_b128 v[188:191], v178 offset:2048
	ds_read_b128 v[192:195], v178 offset:3072
	ds_read_b128 v[214:217], v178 offset:4096
	ds_read_b128 v[218:221], v178 offset:5120
	ds_read_b128 v[222:225], v178 offset:6144
	ds_read_b128 v[226:229], v178 offset:7168
	global_load_lds_dwordx4 v[158:159], off
	v_lshl_add_u64 v[158:159], s[18:19], 0, v[156:157]
	s_add_i32 m0, s17, 0xe000
	s_nop 0
	global_load_lds_dwordx4 v[158:159], off
	s_waitcnt lgkmcnt(8)
	s_barrier
	s_waitcnt lgkmcnt(0)
	s_setprio 1
	s_waitcnt lgkmcnt(0)
	v_mfma_f32_16x16x32_bf16 v[124:127], v[128:131], v[180:183], v[124:127]
	v_mfma_f32_16x16x32_bf16 v[120:123], v[136:139], v[180:183], v[120:123]
	v_mfma_f32_16x16x32_bf16 v[108:111], v[128:131], v[188:191], v[108:111]
	v_mfma_f32_16x16x32_bf16 v[104:107], v[136:139], v[188:191], v[104:107]
	v_mfma_f32_16x16x32_bf16 v[92:95], v[128:131], v[214:217], v[92:95]
	v_mfma_f32_16x16x32_bf16 v[88:91], v[136:139], v[214:217], v[88:91]
	v_mfma_f32_16x16x32_bf16 v[76:79], v[128:131], v[222:225], v[76:79]
	v_mfma_f32_16x16x32_bf16 v[72:75], v[136:139], v[222:225], v[72:75]
	v_mfma_f32_16x16x32_bf16 v[124:127], v[132:135], v[184:187], v[124:127]
	v_mfma_f32_16x16x32_bf16 v[120:123], v[140:143], v[184:187], v[120:123]
	v_mfma_f32_16x16x32_bf16 v[108:111], v[132:135], v[192:195], v[108:111]
	v_mfma_f32_16x16x32_bf16 v[104:107], v[140:143], v[192:195], v[104:107]
	v_mfma_f32_16x16x32_bf16 v[92:95], v[132:135], v[218:221], v[92:95]
	v_mfma_f32_16x16x32_bf16 v[88:91], v[140:143], v[218:221], v[88:91]
	v_mfma_f32_16x16x32_bf16 v[76:79], v[132:135], v[226:229], v[76:79]
	v_mfma_f32_16x16x32_bf16 v[72:75], v[140:143], v[226:229], v[72:75]
	s_setprio 0
	s_barrier
	s_add_i32 s44, 0, 0x14000
	v_add_u32_e32 v158, s44, v176
	s_add_i32 s41, s41, s26
	ds_read_b128 v[230:233], v158
	ds_read_b128 v[234:237], v158 offset:1024
	ds_read_b128 v[238:241], v158 offset:2048
	ds_read_b128 v[242:245], v158 offset:3072
	v_lshl_add_u64 v[158:159], s[20:21], 0, v[160:161]
	s_mov_b32 m0, s41
	v_lshl_add_u64 v[174:175], s[20:21], 0, v[144:145]
	global_load_lds_dwordx4 v[158:159], off
	s_add_i32 m0, s41, 0x2000
	s_nop 0
	global_load_lds_dwordx4 v[174:175], off
	s_barrier
	s_waitcnt lgkmcnt(0)
	s_setprio 1
	s_waitcnt lgkmcnt(0)
	v_mfma_f32_16x16x32_bf16 v[116:119], v[230:233], v[180:183], v[116:119]
	v_mfma_f32_16x16x32_bf16 v[112:115], v[238:241], v[180:183], v[112:115]
	v_mfma_f32_16x16x32_bf16 v[100:103], v[230:233], v[188:191], v[100:103]
	v_mfma_f32_16x16x32_bf16 v[96:99], v[238:241], v[188:191], v[96:99]
	v_mfma_f32_16x16x32_bf16 v[84:87], v[230:233], v[214:217], v[84:87]
	v_mfma_f32_16x16x32_bf16 v[80:83], v[238:241], v[214:217], v[80:83]
	v_mfma_f32_16x16x32_bf16 v[68:71], v[230:233], v[222:225], v[68:71]
	v_mfma_f32_16x16x32_bf16 v[64:67], v[238:241], v[222:225], v[64:67]
	v_mfma_f32_16x16x32_bf16 v[116:119], v[234:237], v[184:187], v[116:119]
	v_mfma_f32_16x16x32_bf16 v[112:115], v[242:245], v[184:187], v[112:115]
	v_mfma_f32_16x16x32_bf16 v[100:103], v[234:237], v[192:195], v[100:103]
	v_mfma_f32_16x16x32_bf16 v[96:99], v[242:245], v[192:195], v[96:99]
	v_mfma_f32_16x16x32_bf16 v[84:87], v[234:237], v[218:221], v[84:87]
	v_mfma_f32_16x16x32_bf16 v[80:83], v[242:245], v[218:221], v[80:83]
	v_mfma_f32_16x16x32_bf16 v[68:71], v[234:237], v[226:229], v[68:71]
	v_mfma_f32_16x16x32_bf16 v[64:67], v[242:245], v[226:229], v[64:67]
	s_setprio 0
	s_mov_b32 m0, s17
	v_lshl_add_u64 v[196:197], s[22:23], 0, v[160:161]
	s_barrier
	ds_read_b128 v[180:183], v178 offset:16384
	ds_read_b128 v[184:187], v178 offset:17408
	ds_read_b128 v[188:191], v178 offset:18432
	ds_read_b128 v[192:195], v178 offset:19456
	ds_read_b128 v[214:217], v178 offset:20480
	ds_read_b128 v[218:221], v178 offset:21504
	ds_read_b128 v[222:225], v178 offset:22528
	ds_read_b128 v[226:229], v178 offset:23552
	global_load_lds_dwordx4 v[196:197], off
	v_lshl_add_u64 v[246:247], s[22:23], 0, v[144:145]
	s_mov_b32 m0, s27
	s_nop 0
	global_load_lds_dwordx4 v[246:247], off
	s_barrier
	s_waitcnt lgkmcnt(0)
	s_setprio 1
	s_waitcnt lgkmcnt(0)
	v_mfma_f32_16x16x32_bf16 v[60:63], v[128:131], v[180:183], v[60:63]
	v_mfma_f32_16x16x32_bf16 v[56:59], v[136:139], v[180:183], v[56:59]
	v_mfma_f32_16x16x32_bf16 v[44:47], v[128:131], v[188:191], v[44:47]
	v_mfma_f32_16x16x32_bf16 v[40:43], v[136:139], v[188:191], v[40:43]
	v_mfma_f32_16x16x32_bf16 v[28:31], v[128:131], v[214:217], v[28:31]
	v_mfma_f32_16x16x32_bf16 v[24:27], v[136:139], v[214:217], v[24:27]
	v_mfma_f32_16x16x32_bf16 v[12:15], v[128:131], v[222:225], v[12:15]
	v_mfma_f32_16x16x32_bf16 v[8:11], v[136:139], v[222:225], v[8:11]
	v_mfma_f32_16x16x32_bf16 v[60:63], v[132:135], v[184:187], v[60:63]
	v_mfma_f32_16x16x32_bf16 v[56:59], v[140:143], v[184:187], v[56:59]
	v_mfma_f32_16x16x32_bf16 v[44:47], v[132:135], v[192:195], v[44:47]
	v_mfma_f32_16x16x32_bf16 v[40:43], v[140:143], v[192:195], v[40:43]
	v_mfma_f32_16x16x32_bf16 v[28:31], v[132:135], v[218:221], v[28:31]
	v_mfma_f32_16x16x32_bf16 v[24:27], v[140:143], v[218:221], v[24:27]
	v_mfma_f32_16x16x32_bf16 v[12:15], v[132:135], v[226:229], v[12:15]
	v_mfma_f32_16x16x32_bf16 v[8:11], v[140:143], v[226:229], v[8:11]
	s_setprio 0
	s_barrier
; #define PG8_STAGE(bufoff, gbase, voff) do { _Pragma("unroll") for (int _i = 0; _i < 2; ++_i) \
;         __builtin_amdgcn_global_load_lds((const unsigned*)((const char*)(gbase) + (voff)[_i]), (LAS unsigned*)(lds + (bufoff) + ldsw + _i * 8192), 16, 0, 0); } while (0)
; #define PG8_LDA(dst, b, h) do { _Pragma("unroll") for (int m = 0; m < 4; ++m) _Pragma("unroll") for (int k = 0; k < 2; ++k) dst[m][k] = *(const LAS bf16x8*)(lds + PG8_SA(b, h) + aoff + m * 2048 + k * 1024); } while (0)
; #define PG8_LDB(dst, b, h) do { _Pragma("unroll") for (int n = 0; n < 2; ++n) _Pragma("unroll") for (int k = 0; k < 2; ++k) dst[n][k] = *(const LAS bf16x8*)(lds + PG8_SB(b, h) + boff + n * 2048 + k * 1024); } while (0)
; #define PG8_MMA(ai, bj, At, Bt) do { __builtin_amdgcn_s_setprio(1); _Pragma("unroll") for (int m = 0; m < 4; ++m) _Pragma("unroll") for (int n = 0; n < 2; ++n) _Pragma("unroll") for (int k = 0; k < 2; ++k) \
;         acc[ai][bj][m][n] = __builtin_amdgcn_mfma_f32_16x16x32_bf16(Bt[n][k], At[m][k], acc[ai][bj][m][n], 0, 0, 0); __builtin_amdgcn_s_setprio(0); } while (0)
; #define PG8_WAIT_V(n) asm volatile("s_waitcnt vmcnt(" #n ")" ::: "memory")
; #define PG8_WAIT_L(n) asm volatile("s_waitcnt lgkmcnt(" #n ")" ::: "memory")
; #define PG8_BAR __builtin_amdgcn_s_barrier()
; #define PG8_SCHED __builtin_amdgcn_sched_barrier(0)
; template <class Epi>
; DEV void gemm_phase(LAS unsigned char* lds, const Gemm g, const StaticOrder& S, const Epi& E) {
;     ...
;             PG8_BAR; PG8_WAIT_L(0); PG8_MMA(1, 0, At, B0); PG8_BAR; PG8_SCHED;
;             PG8_STAGE(PG8_SB(0, 1), b2 + hstep, voffB);
;             PG8_WAIT_V(6); PG8_BAR; PG8_MMA(1, 1, At, B1); PG8_BAR;
;             PG8_LDB(B0, 1, 0); PG8_SCHED; PG8_LDA(At, 1, 0); PG8_STAGE(PG8_SA(0, 1), a2 + hstep, voffA);
;             PG8_WAIT_L(8); PG8_BAR; PG8_WAIT_L(0); PG8_MMA(0, 0, At, B0); PG8_BAR; PG8_SCHED;
;             PG8_LDB(B1, 1, 1); PG8_STAGE(PG8_SB(1, 0), b3, voffB);
;             PG8_BAR; PG8_WAIT_L(0); PG8_MMA(0, 1, At, B1); PG8_BAR;
	s_add_u32 s42, s20, 0x80000
	s_addc_u32 s43, s21, 0
	s_add_i32 s41, s44, s26
	v_lshl_add_u64 v[128:129], s[42:43], 0, v[160:161]
	s_mov_b32 m0, s41
	s_nop 0
	global_load_lds_dwordx4 v[128:129], off
	v_lshl_add_u64 v[128:129], s[42:43], 0, v[144:145]
	s_add_i32 m0, s41, 0x2000
	s_nop 0
	global_load_lds_dwordx4 v[128:129], off
	s_waitcnt vmcnt(6)
	s_barrier
	s_setprio 1
	v_mfma_f32_16x16x32_bf16 v[52:55], v[230:233], v[180:183], v[52:55]
	v_mfma_f32_16x16x32_bf16 v[48:51], v[238:241], v[180:183], v[48:51]
	v_mfma_f32_16x16x32_bf16 v[36:39], v[230:233], v[188:191], v[36:39]
	v_mfma_f32_16x16x32_bf16 v[32:35], v[238:241], v[188:191], v[32:35]
	v_mfma_f32_16x16x32_bf16 v[20:23], v[230:233], v[214:217], v[20:23]
	v_mfma_f32_16x16x32_bf16 v[16:19], v[238:241], v[214:217], v[16:19]
	v_mfma_f32_16x16x32_bf16 v[4:7], v[230:233], v[222:225], v[4:7]
	v_mfma_f32_16x16x32_bf16 v[0:3], v[238:241], v[222:225], v[0:3]
	v_mfma_f32_16x16x32_bf16 v[52:55], v[234:237], v[184:187], v[52:55]
	v_mfma_f32_16x16x32_bf16 v[48:51], v[242:245], v[184:187], v[48:51]
	v_mfma_f32_16x16x32_bf16 v[36:39], v[234:237], v[192:195], v[36:39]
	v_mfma_f32_16x16x32_bf16 v[32:35], v[242:245], v[192:195], v[32:35]
	v_mfma_f32_16x16x32_bf16 v[20:23], v[234:237], v[218:221], v[20:23]
	v_mfma_f32_16x16x32_bf16 v[16:19], v[242:245], v[218:221], v[16:19]
	v_mfma_f32_16x16x32_bf16 v[4:7], v[234:237], v[226:229], v[4:7]
	v_mfma_f32_16x16x32_bf16 v[0:3], v[242:245], v[226:229], v[0:3]
	s_setprio 0
	s_add_i32 s41, 0, 0x18000
	v_add_u32_e32 v140, s41, v176
	s_barrier
	ds_read_b128 v[128:131], v140
	ds_read_b128 v[132:135], v140 offset:1024
	ds_read_b128 v[136:139], v140 offset:2048
	ds_read_b128 v[140:143], v140 offset:3072
	s_add_u32 s22, s22, 0x80000
	s_addc_u32 s23, s23, 0
	s_mov_b32 m0, s28
	v_lshl_add_u64 v[230:231], s[22:23], 0, v[160:161]
	ds_read_b128 v[180:183], v178 offset:32768
	ds_read_b128 v[184:187], v178 offset:33792
	ds_read_b128 v[188:191], v178 offset:34816
	ds_read_b128 v[192:195], v178 offset:35840
	ds_read_b128 v[214:217], v178 offset:36864
	ds_read_b128 v[218:221], v178 offset:37888
	ds_read_b128 v[222:225], v178 offset:38912
	ds_read_b128 v[226:229], v178 offset:39936
	global_load_lds_dwordx4 v[230:231], off
	v_lshl_add_u64 v[230:231], s[22:23], 0, v[144:145]
	s_mov_b32 m0, s29
	s_nop 0
	global_load_lds_dwordx4 v[230:231], off
	s_waitcnt lgkmcnt(8)
	s_barrier
	s_waitcnt lgkmcnt(0)
	s_setprio 1
	s_waitcnt lgkmcnt(0)
	v_mfma_f32_16x16x32_bf16 v[124:127], v[128:131], v[180:183], v[124:127]
	v_mfma_f32_16x16x32_bf16 v[120:123], v[136:139], v[180:183], v[120:123]
	v_mfma_f32_16x16x32_bf16 v[108:111], v[128:131], v[188:191], v[108:111]
	v_mfma_f32_16x16x32_bf16 v[104:107], v[136:139], v[188:191], v[104:107]
	v_mfma_f32_16x16x32_bf16 v[92:95], v[128:131], v[214:217], v[92:95]
	v_mfma_f32_16x16x32_bf16 v[88:91], v[136:139], v[214:217], v[88:91]
	v_mfma_f32_16x16x32_bf16 v[76:79], v[128:131], v[222:225], v[76:79]
	v_mfma_f32_16x16x32_bf16 v[72:75], v[136:139], v[222:225], v[72:75]
	v_mfma_f32_16x16x32_bf16 v[124:127], v[132:135], v[184:187], v[124:127]
	v_mfma_f32_16x16x32_bf16 v[120:123], v[140:143], v[184:187], v[120:123]
	v_mfma_f32_16x16x32_bf16 v[108:111], v[132:135], v[192:195], v[108:111]
	v_mfma_f32_16x16x32_bf16 v[104:107], v[140:143], v[192:195], v[104:107]
	v_mfma_f32_16x16x32_bf16 v[92:95], v[132:135], v[218:221], v[92:95]
	v_mfma_f32_16x16x32_bf16 v[88:91], v[140:143], v[218:221], v[88:91]
	v_mfma_f32_16x16x32_bf16 v[76:79], v[132:135], v[226:229], v[76:79]
	v_mfma_f32_16x16x32_bf16 v[72:75], v[140:143], v[226:229], v[72:75]
	s_setprio 0
	s_barrier
	s_add_i32 s22, 0, 0x1c000
	s_add_i32 s23, s41, s26
	v_add_u32_e32 v179, s22, v176
	v_lshl_add_u64 v[158:159], v[158:159], 0, s[2:3]
	s_mov_b32 m0, s23
	ds_read_b128 v[230:233], v179
	ds_read_b128 v[234:237], v179 offset:1024
	ds_read_b128 v[238:241], v179 offset:2048
	ds_read_b128 v[242:245], v179 offset:3072
	global_load_lds_dwordx4 v[158:159], off
	v_lshl_add_u64 v[158:159], v[174:175], 0, s[2:3]
	s_add_i32 m0, s23, 0x2000
	s_nop 0
	global_load_lds_dwordx4 v[158:159], off
	s_barrier
	s_waitcnt lgkmcnt(0)
	s_setprio 1
	s_waitcnt lgkmcnt(0)
	v_mfma_f32_16x16x32_bf16 v[116:119], v[230:233], v[180:183], v[116:119]
	v_mfma_f32_16x16x32_bf16 v[112:115], v[238:241], v[180:183], v[112:115]
	v_mfma_f32_16x16x32_bf16 v[100:103], v[230:233], v[188:191], v[100:103]
	v_mfma_f32_16x16x32_bf16 v[96:99], v[238:241], v[188:191], v[96:99]
	v_mfma_f32_16x16x32_bf16 v[84:87], v[230:233], v[214:217], v[84:87]
	v_mfma_f32_16x16x32_bf16 v[80:83], v[238:241], v[214:217], v[80:83]
	v_mfma_f32_16x16x32_bf16 v[68:71], v[230:233], v[222:225], v[68:71]
	v_mfma_f32_16x16x32_bf16 v[64:67], v[238:241], v[222:225], v[64:67]
	v_mfma_f32_16x16x32_bf16 v[116:119], v[234:237], v[184:187], v[116:119]
	v_mfma_f32_16x16x32_bf16 v[112:115], v[242:245], v[184:187], v[112:115]
	v_mfma_f32_16x16x32_bf16 v[100:103], v[234:237], v[192:195], v[100:103]
	v_mfma_f32_16x16x32_bf16 v[96:99], v[242:245], v[192:195], v[96:99]
	v_mfma_f32_16x16x32_bf16 v[84:87], v[234:237], v[218:221], v[84:87]
	v_mfma_f32_16x16x32_bf16 v[80:83], v[242:245], v[218:221], v[80:83]
	v_mfma_f32_16x16x32_bf16 v[68:71], v[234:237], v[226:229], v[68:71]
	v_mfma_f32_16x16x32_bf16 v[64:67], v[242:245], v[226:229], v[64:67]
	s_setprio 0
	s_mov_b32 m0, s30
	v_lshl_add_u64 v[158:159], v[196:197], 0, s[2:3]
	s_barrier
; #define PG8_STAGE(bufoff, gbase, voff) do { _Pragma("unroll") for (int _i = 0; _i < 2; ++_i) \
;         __builtin_amdgcn_global_load_lds((const unsigned*)((const char*)(gbase) + (voff)[_i]), (LAS unsigned*)(lds + (bufoff) + ldsw + _i * 8192), 16, 0, 0); } while (0)
; #define PG8_LDA(dst, b, h) do { _Pragma("unroll") for (int m = 0; m < 4; ++m) _Pragma("unroll") for (int k = 0; k < 2; ++k) dst[m][k] = *(const LAS bf16x8*)(lds + PG8_SA(b, h) + aoff + m * 2048 + k * 1024); } while (0)
; #define PG8_MMA(ai, bj, At, Bt) do { __builtin_amdgcn_s_setprio(1); _Pragma("unroll") for (int m = 0; m < 4; ++m) _Pragma("unroll") for (int n = 0; n < 2; ++n) _Pragma("unroll") for (int k = 0; k < 2; ++k) \
;         acc[ai][bj][m][n] = __builtin_amdgcn_mfma_f32_16x16x32_bf16(Bt[n][k], At[m][k], acc[ai][bj][m][n], 0, 0, 0); __builtin_amdgcn_s_setprio(0); } while (0)
; #define PG8_WAIT_V(n) asm volatile("s_waitcnt vmcnt(" #n ")" ::: "memory")
; #define PG8_WAIT_L(n) asm volatile("s_waitcnt lgkmcnt(" #n ")" ::: "memory")
; #define PG8_BAR __builtin_amdgcn_s_barrier()
; #define PG8_SCHED __builtin_amdgcn_sched_barrier(0)
; template <class Epi>
; DEV void gemm_phase(LAS unsigned char* lds, const Gemm g, const StaticOrder& S, const Epi& E) {
;     ...
;             PG8_BAR; PG8_WAIT_L(0); PG8_MMA(0, 1, At, B1); PG8_BAR;
;             PG8_LDA(At, 1, 1); PG8_STAGE(PG8_SA(1, 0), a3, voffA);
;             PG8_BAR; PG8_WAIT_L(0); PG8_MMA(1, 0, At, B0); PG8_BAR; PG8_SCHED;
;             PG8_STAGE(PG8_SB(1, 1), b3 + hstep, voffB);
;             PG8_WAIT_V(6); PG8_BAR; PG8_MMA(1, 1, At, B1); PG8_BAR;
;     DEV void operator()(AccRef acc, const pg8::Unit& u, int wr, int wc, int fr, int fq) const {
;     ...
;             for (int m = 0; m < 4; ++m) { const int row = row0 + ai * 128 + m * 16; u16* rowp = O + (size_t)row * 2560 + col0; const float rs = rowscale(ss, row);
;                 f32x4 cs = (f32x4){1.f, 1.f, 1.f, 1.f}, sn = (f32x4){0.f, 0.f, 0.f, 0.f};
;                 if (rope) { cs = *(const f32x4*)(cosT + row * 8 + 4 * (fq & 1)); sn = *(const f32x4*)(sinT + row * 8 + 4 * (fq & 1)); }
	ds_read_b128 v[180:183], v178 offset:49152
	ds_read_b128 v[184:187], v178 offset:50176
	ds_read_b128 v[188:191], v178 offset:51200
	ds_read_b128 v[192:195], v178 offset:52224
	ds_read_b128 v[214:217], v178 offset:53248
	ds_read_b128 v[218:221], v178 offset:54272
	ds_read_b128 v[222:225], v178 offset:55296
	ds_read_b128 v[226:229], v178 offset:56320
	global_load_lds_dwordx4 v[158:159], off
	v_lshl_add_u64 v[158:159], v[246:247], 0, s[2:3]
	s_mov_b32 m0, s31
	s_nop 0
	global_load_lds_dwordx4 v[158:159], off
	s_barrier
	s_waitcnt lgkmcnt(0)
	s_setprio 1
	s_waitcnt lgkmcnt(0)
	v_mfma_f32_16x16x32_bf16 v[60:63], v[128:131], v[180:183], v[60:63]
	v_mfma_f32_16x16x32_bf16 v[56:59], v[136:139], v[180:183], v[56:59]
	v_mfma_f32_16x16x32_bf16 v[44:47], v[128:131], v[188:191], v[44:47]
	v_mfma_f32_16x16x32_bf16 v[40:43], v[136:139], v[188:191], v[40:43]
	v_mfma_f32_16x16x32_bf16 v[28:31], v[128:131], v[214:217], v[28:31]
	v_mfma_f32_16x16x32_bf16 v[24:27], v[136:139], v[214:217], v[24:27]
	v_mfma_f32_16x16x32_bf16 v[12:15], v[128:131], v[222:225], v[12:15]
	v_mfma_f32_16x16x32_bf16 v[8:11], v[136:139], v[222:225], v[8:11]
	v_mfma_f32_16x16x32_bf16 v[60:63], v[132:135], v[184:187], v[60:63]
	v_mfma_f32_16x16x32_bf16 v[56:59], v[140:143], v[184:187], v[56:59]
	v_mfma_f32_16x16x32_bf16 v[44:47], v[132:135], v[192:195], v[44:47]
	v_mfma_f32_16x16x32_bf16 v[40:43], v[140:143], v[192:195], v[40:43]
	v_mfma_f32_16x16x32_bf16 v[28:31], v[132:135], v[218:221], v[28:31]
	v_mfma_f32_16x16x32_bf16 v[24:27], v[140:143], v[218:221], v[24:27]
	v_mfma_f32_16x16x32_bf16 v[12:15], v[132:135], v[226:229], v[12:15]
	v_mfma_f32_16x16x32_bf16 v[8:11], v[140:143], v[226:229], v[8:11]
	s_setprio 0
	s_barrier
	s_add_u32 s20, s20, 0x80080
	s_addc_u32 s21, s21, 0
	s_add_i32 s22, s22, s26
	v_lshl_add_u64 v[128:129], s[20:21], 0, v[160:161]
	s_mov_b32 m0, s22
	s_nop 0
	global_load_lds_dwordx4 v[128:129], off
	v_lshl_add_u64 v[128:129], s[20:21], 0, v[144:145]
	s_add_i32 m0, s22, 0x2000
	s_nop 0
	global_load_lds_dwordx4 v[128:129], off
	s_waitcnt vmcnt(6)
	s_barrier
	s_setprio 1
	v_mfma_f32_16x16x32_bf16 v[52:55], v[230:233], v[180:183], v[52:55]
	v_mfma_f32_16x16x32_bf16 v[48:51], v[238:241], v[180:183], v[48:51]
	v_mfma_f32_16x16x32_bf16 v[36:39], v[230:233], v[188:191], v[36:39]
	v_mfma_f32_16x16x32_bf16 v[32:35], v[238:241], v[188:191], v[32:35]
	v_mfma_f32_16x16x32_bf16 v[20:23], v[230:233], v[214:217], v[20:23]
	v_mfma_f32_16x16x32_bf16 v[16:19], v[238:241], v[214:217], v[16:19]
	v_mfma_f32_16x16x32_bf16 v[4:7], v[230:233], v[222:225], v[4:7]
	v_mfma_f32_16x16x32_bf16 v[0:3], v[238:241], v[222:225], v[0:3]
	v_mfma_f32_16x16x32_bf16 v[52:55], v[234:237], v[184:187], v[52:55]
	v_mfma_f32_16x16x32_bf16 v[48:51], v[242:245], v[184:187], v[48:51]
	v_mfma_f32_16x16x32_bf16 v[36:39], v[234:237], v[192:195], v[36:39]
	v_mfma_f32_16x16x32_bf16 v[32:35], v[242:245], v[192:195], v[32:35]
	v_mfma_f32_16x16x32_bf16 v[20:23], v[234:237], v[218:221], v[20:23]
	v_mfma_f32_16x16x32_bf16 v[16:19], v[242:245], v[218:221], v[16:19]
	v_mfma_f32_16x16x32_bf16 v[4:7], v[234:237], v[226:229], v[4:7]
	v_mfma_f32_16x16x32_bf16 v[0:3], v[242:245], v[226:229], v[0:3]
	s_setprio 0
	s_add_i32 s40, s40, 2
	s_add_u32 s18, s18, 0x100
	s_addc_u32 s19, s19, 0
	s_add_u32 s38, s38, 0x100
	s_addc_u32 s39, s39, 0
	s_cmp_gt_u32 s40, 29
	s_barrier
	s_cbranch_scc0 .LBB0_152
	v_lshl_add_u32 v174, s4, 8, v167
	v_ashrrev_i32_e32 v175, 31, v174
	v_readlane_b32 s20, v250, 47
	v_readlane_b32 s21, v250, 48
	v_lshlrev_b32_e32 v248, 5, v174
	v_mov_b32_e32 v249, 0
	v_lshl_add_u64 v[246:247], v[152:153], 0, v[248:249]
	global_load_dword v255, v[246:247], off
	global_load_dword v255, v[246:247], off offset:512
	global_load_dword v255, v[246:247], off offset:1024
	global_load_dword v255, v[246:247], off offset:1536
	v_lshl_add_u64 v[246:247], v[150:151], 0, v[248:249]
	global_load_dword v255, v[246:247], off
	global_load_dword v255, v[246:247], off offset:512
	global_load_dword v255, v[246:247], off offset:1024
	global_load_dword v255, v[246:247], off offset:1536
	v_add_u32_e32 v249, 0x1000, v248
	v_mov_b32_e32 v128, v249
	v_mov_b32_e32 v129, 0
	v_lshl_add_u64 v[246:247], v[152:153], 0, v[128:129]
	global_load_dword v255, v[246:247], off
	global_load_dword v255, v[246:247], off offset:512
	global_load_dword v255, v[246:247], off offset:1024
	global_load_dword v255, v[246:247], off offset:1536
	v_lshl_add_u64 v[246:247], v[150:151], 0, v[128:129]
	global_load_dword v255, v[246:247], off
	global_load_dword v255, v[246:247], off offset:512
	global_load_dword v255, v[246:247], off offset:1024
	global_load_dword v255, v[246:247], off offset:1536
	global_load_dword v255, v248, s[20:21]
	global_load_dword v255, v248, s[20:21] offset:512
	global_load_dword v255, v248, s[20:21] offset:1024
	global_load_dword v255, v248, s[20:21] offset:1536
	v_mov_b32_e32 v248, v249
	global_load_dword v255, v248, s[20:21]
	global_load_dword v255, v248, s[20:21] offset:512
	global_load_dword v255, v248, s[20:21] offset:1024
	global_load_dword v255, v248, s[20:21] offset:1536
	v_lshlrev_b64 v[128:129], 5, v[174:175]
	s_cmp_lt_i32 s16, 9
	s_cselect_b64 s[4:5], -1, 0
	v_lshl_add_u64 v[128:129], s[20:21], 0, v[128:129]
	global_load_dwordx4 v[136:139], v[128:129], off offset:16
	global_load_dwordx4 v[140:143], v[128:129], off
	s_and_b64 s[18:19], s[6:7], s[4:5]
	v_cndmask_b32_e64 v128, 0, 1, s[18:19]
	v_cmp_ne_u32_e64 s[4:5], 1, v128
	s_andn2_b64 vcc, exec, s[18:19]
	s_cbranch_vccnz .LBB0_155
	v_lshlrev_b32_e32 v128, 3, v174
	v_ashrrev_i32_e32 v129, 31, v128
	v_lshlrev_b64 v[128:129], 2, v[128:129]
	v_lshl_add_u64 v[130:131], v[152:153], 0, v[128:129]
	v_lshl_add_u64 v[132:133], v[150:151], 0, v[128:129]
	global_load_dwordx4 v[128:131], v[130:131], off
	s_nop 0
	global_load_dwordx4 v[132:135], v[132:133], off
	s_branch .LBB0_156

; #define PG8_STAGE(bufoff, gbase, voff) do { _Pragma("unroll") for (int _i = 0; _i < 2; ++_i) \
;         __builtin_amdgcn_global_load_lds((const unsigned*)((const char*)(gbase) + (voff)[_i]), (LAS unsigned*)(lds + (bufoff) + ldsw + _i * 8192), 16, 0, 0); } while (0)
; #define PG8_LDA(dst, b, h) do { _Pragma("unroll") for (int m = 0; m < 4; ++m) _Pragma("unroll") for (int k = 0; k < 2; ++k) dst[m][k] = *(const LAS bf16x8*)(lds + PG8_SA(b, h) + aoff + m * 2048 + k * 1024); } while (0)
; #define PG8_LDB(dst, b, h) do { _Pragma("unroll") for (int n = 0; n < 2; ++n) _Pragma("unroll") for (int k = 0; k < 2; ++k) dst[n][k] = *(const LAS bf16x8*)(lds + PG8_SB(b, h) + boff + n * 2048 + k * 1024); } while (0)
; #define PG8_MMA(ai, bj, At, Bt) do { __builtin_amdgcn_s_setprio(1); _Pragma("unroll") for (int m = 0; m < 4; ++m) _Pragma("unroll") for (int n = 0; n < 2; ++n) _Pragma("unroll") for (int k = 0; k < 2; ++k) \
;         acc[ai][bj][m][n] = __builtin_amdgcn_mfma_f32_16x16x32_bf16(Bt[n][k], At[m][k], acc[ai][bj][m][n], 0, 0, 0); __builtin_amdgcn_s_setprio(0); } while (0)
; #define PG8_WAIT_L(n) asm volatile("s_waitcnt lgkmcnt(" #n ")" ::: "memory")
; #define PG8_BAR __builtin_amdgcn_s_barrier()
; #define PG8_SCHED __builtin_amdgcn_sched_barrier(0)
; template <class Epi>
; DEV void gemm_phase(LAS unsigned char* lds, const Gemm g, const StaticOrder& S, const Epi& E) {
;     ...
;             PG8_LDB(B0, 0, 0); PG8_SCHED; PG8_LDA(At, 0, 0); PG8_STAGE(PG8_SA(1, 1), a1 + hstep, voffA);
;             PG8_WAIT_L(8); PG8_BAR; PG8_WAIT_L(0); PG8_MMA(0, 0, At, B0); PG8_BAR; PG8_SCHED;
;             PG8_LDB(B1, 0, 1); PG8_STAGE(PG8_SB(0, 0), b2, voffB);
;             PG8_BAR; PG8_WAIT_L(0); PG8_MMA(0, 1, At, B1); PG8_BAR;
;             PG8_LDA(At, 0, 1); PG8_STAGE(PG8_SA(0, 0), a2, voffA);
;             PG8_BAR; PG8_WAIT_L(0); PG8_MMA(1, 0, At, B0); PG8_BAR; PG8_SCHED;
.LBB0_344:
	s_add_u32 s20, s18, 0xfff80080
	s_addc_u32 s21, s19, -1
	s_add_i32 s45, 0, 0x10000
	v_add_u32_e32 v146, s45, v149
	ds_read_b128 v[128:131], v146
	ds_read_b128 v[132:135], v146 offset:1024
	ds_read_b128 v[142:145], v146 offset:2048
	ds_read_b128 v[150:153], v146 offset:3072
	s_cmp_eq_u32 s44, 28
	s_cselect_b32 s23, s1, s21
	s_cselect_b32 s22, s13, s20
	s_cselect_b32 s21, s11, s43
	s_cselect_b32 s20, s41, s42
	v_lshl_add_u64 v[154:155], s[18:19], 0, v[138:139]
	s_add_i32 m0, s30, 0xc000
	ds_read_b128 v[174:177], v159
	ds_read_b128 v[178:181], v159 offset:1024
	ds_read_b128 v[182:185], v159 offset:2048
	ds_read_b128 v[186:189], v159 offset:3072
	ds_read_b128 v[190:193], v159 offset:4096
	ds_read_b128 v[194:197], v159 offset:5120
	ds_read_b128 v[214:217], v159 offset:6144
	ds_read_b128 v[218:221], v159 offset:7168
	global_load_lds_dwordx4 v[154:155], off
	v_lshl_add_u64 v[154:155], s[18:19], 0, v[140:141]
	s_add_i32 m0, s30, 0xe000
	s_nop 0
	global_load_lds_dwordx4 v[154:155], off
	s_waitcnt lgkmcnt(8)
	s_barrier
	s_waitcnt lgkmcnt(0)
	s_setprio 1
	s_waitcnt lgkmcnt(0)
	v_mfma_f32_16x16x32_bf16 v[124:127], v[128:131], v[174:177], v[124:127]
	v_mfma_f32_16x16x32_bf16 v[120:123], v[142:145], v[174:177], v[120:123]
	v_mfma_f32_16x16x32_bf16 v[116:119], v[128:131], v[182:185], v[116:119]
	v_mfma_f32_16x16x32_bf16 v[108:111], v[142:145], v[182:185], v[108:111]
	v_mfma_f32_16x16x32_bf16 v[100:103], v[128:131], v[190:193], v[100:103]
	v_mfma_f32_16x16x32_bf16 v[92:95], v[142:145], v[190:193], v[92:95]
	v_mfma_f32_16x16x32_bf16 v[84:87], v[128:131], v[214:217], v[84:87]
	v_mfma_f32_16x16x32_bf16 v[76:79], v[142:145], v[214:217], v[76:79]
	v_mfma_f32_16x16x32_bf16 v[124:127], v[132:135], v[178:181], v[124:127]
	v_mfma_f32_16x16x32_bf16 v[120:123], v[150:153], v[178:181], v[120:123]
	v_mfma_f32_16x16x32_bf16 v[116:119], v[132:135], v[186:189], v[116:119]
	v_mfma_f32_16x16x32_bf16 v[108:111], v[150:153], v[186:189], v[108:111]
	v_mfma_f32_16x16x32_bf16 v[100:103], v[132:135], v[194:197], v[100:103]
	v_mfma_f32_16x16x32_bf16 v[92:95], v[150:153], v[194:197], v[92:95]
	v_mfma_f32_16x16x32_bf16 v[84:87], v[132:135], v[218:221], v[84:87]
	v_mfma_f32_16x16x32_bf16 v[76:79], v[150:153], v[218:221], v[76:79]
	s_setprio 0
	s_barrier
	s_add_i32 s48, 0, 0x14000
	s_add_i32 s45, s45, s29
	v_add_u32_e32 v146, s48, v149
	v_lshl_add_u64 v[154:155], s[20:21], 0, v[160:161]
	s_mov_b32 m0, s45
	ds_read_b128 v[222:225], v146
	ds_read_b128 v[226:229], v146 offset:1024
	ds_read_b128 v[230:233], v146 offset:2048
	ds_read_b128 v[234:237], v146 offset:3072
	global_load_lds_dwordx4 v[154:155], off
	v_lshl_add_u64 v[238:239], s[20:21], 0, v[136:137]
	s_add_i32 m0, s45, 0x2000
	s_nop 0
	global_load_lds_dwordx4 v[238:239], off
	s_barrier
	s_waitcnt lgkmcnt(0)
	s_setprio 1
	s_waitcnt lgkmcnt(0)
	v_mfma_f32_16x16x32_bf16 v[112:115], v[222:225], v[174:177], v[112:115]
	v_mfma_f32_16x16x32_bf16 v[104:107], v[230:233], v[174:177], v[104:107]
	v_mfma_f32_16x16x32_bf16 v[96:99], v[222:225], v[182:185], v[96:99]
	v_mfma_f32_16x16x32_bf16 v[88:91], v[230:233], v[182:185], v[88:91]
	v_mfma_f32_16x16x32_bf16 v[80:83], v[222:225], v[190:193], v[80:83]
	v_mfma_f32_16x16x32_bf16 v[72:75], v[230:233], v[190:193], v[72:75]
	v_mfma_f32_16x16x32_bf16 v[68:71], v[222:225], v[214:217], v[68:71]
	v_mfma_f32_16x16x32_bf16 v[64:67], v[230:233], v[214:217], v[64:67]
	v_mfma_f32_16x16x32_bf16 v[112:115], v[226:229], v[178:181], v[112:115]
	v_mfma_f32_16x16x32_bf16 v[104:107], v[234:237], v[178:181], v[104:107]
	v_mfma_f32_16x16x32_bf16 v[96:99], v[226:229], v[186:189], v[96:99]
	v_mfma_f32_16x16x32_bf16 v[88:91], v[234:237], v[186:189], v[88:91]
	v_mfma_f32_16x16x32_bf16 v[80:83], v[226:229], v[194:197], v[80:83]
	v_mfma_f32_16x16x32_bf16 v[72:75], v[234:237], v[194:197], v[72:75]
	v_mfma_f32_16x16x32_bf16 v[68:71], v[226:229], v[218:221], v[68:71]
	v_mfma_f32_16x16x32_bf16 v[64:67], v[234:237], v[218:221], v[64:67]
	s_setprio 0
	s_mov_b32 m0, s30
	v_lshl_add_u64 v[240:241], s[22:23], 0, v[160:161]
	s_barrier
	ds_read_b128 v[174:177], v159 offset:16384
	ds_read_b128 v[178:181], v159 offset:17408
	ds_read_b128 v[182:185], v159 offset:18432
	ds_read_b128 v[186:189], v159 offset:19456
	ds_read_b128 v[190:193], v159 offset:20480
	ds_read_b128 v[194:197], v159 offset:21504
	ds_read_b128 v[214:217], v159 offset:22528
	ds_read_b128 v[218:221], v159 offset:23552
	global_load_lds_dwordx4 v[240:241], off
	v_lshl_add_u64 v[242:243], s[22:23], 0, v[136:137]
	s_mov_b32 m0, s31
	s_nop 0
	global_load_lds_dwordx4 v[242:243], off
	s_barrier
	s_waitcnt lgkmcnt(0)
	s_setprio 1
	s_waitcnt lgkmcnt(0)
	v_mfma_f32_16x16x32_bf16 v[60:63], v[128:131], v[174:177], v[60:63]
	v_mfma_f32_16x16x32_bf16 v[56:59], v[142:145], v[174:177], v[56:59]
	v_mfma_f32_16x16x32_bf16 v[52:55], v[128:131], v[182:185], v[52:55]
	v_mfma_f32_16x16x32_bf16 v[44:47], v[142:145], v[182:185], v[44:47]
	v_mfma_f32_16x16x32_bf16 v[36:39], v[128:131], v[190:193], v[36:39]
	v_mfma_f32_16x16x32_bf16 v[28:31], v[142:145], v[190:193], v[28:31]
	v_mfma_f32_16x16x32_bf16 v[20:23], v[128:131], v[214:217], v[20:23]
	v_mfma_f32_16x16x32_bf16 v[12:15], v[142:145], v[214:217], v[12:15]
	v_mfma_f32_16x16x32_bf16 v[60:63], v[132:135], v[178:181], v[60:63]
	v_mfma_f32_16x16x32_bf16 v[56:59], v[150:153], v[178:181], v[56:59]
	v_mfma_f32_16x16x32_bf16 v[52:55], v[132:135], v[186:189], v[52:55]
	v_mfma_f32_16x16x32_bf16 v[44:47], v[150:153], v[186:189], v[44:47]
	v_mfma_f32_16x16x32_bf16 v[36:39], v[132:135], v[194:197], v[36:39]
	v_mfma_f32_16x16x32_bf16 v[28:31], v[150:153], v[194:197], v[28:31]
	v_mfma_f32_16x16x32_bf16 v[20:23], v[132:135], v[218:221], v[20:23]
	v_mfma_f32_16x16x32_bf16 v[12:15], v[150:153], v[218:221], v[12:15]
	s_setprio 0
	s_barrier
; #define PG8_STAGE(bufoff, gbase, voff) do { _Pragma("unroll") for (int _i = 0; _i < 2; ++_i) \
;         __builtin_amdgcn_global_load_lds((const unsigned*)((const char*)(gbase) + (voff)[_i]), (LAS unsigned*)(lds + (bufoff) + ldsw + _i * 8192), 16, 0, 0); } while (0)
; #define PG8_LDA(dst, b, h) do { _Pragma("unroll") for (int m = 0; m < 4; ++m) _Pragma("unroll") for (int k = 0; k < 2; ++k) dst[m][k] = *(const LAS bf16x8*)(lds + PG8_SA(b, h) + aoff + m * 2048 + k * 1024); } while (0)
; #define PG8_LDB(dst, b, h) do { _Pragma("unroll") for (int n = 0; n < 2; ++n) _Pragma("unroll") for (int k = 0; k < 2; ++k) dst[n][k] = *(const LAS bf16x8*)(lds + PG8_SB(b, h) + boff + n * 2048 + k * 1024); } while (0)
; #define PG8_MMA(ai, bj, At, Bt) do { __builtin_amdgcn_s_setprio(1); _Pragma("unroll") for (int m = 0; m < 4; ++m) _Pragma("unroll") for (int n = 0; n < 2; ++n) _Pragma("unroll") for (int k = 0; k < 2; ++k) \
;         acc[ai][bj][m][n] = __builtin_amdgcn_mfma_f32_16x16x32_bf16(Bt[n][k], At[m][k], acc[ai][bj][m][n], 0, 0, 0); __builtin_amdgcn_s_setprio(0); } while (0)
; #define PG8_WAIT_V(n) asm volatile("s_waitcnt vmcnt(" #n ")" ::: "memory")
; #define PG8_WAIT_L(n) asm volatile("s_waitcnt lgkmcnt(" #n ")" ::: "memory")
; #define PG8_BAR __builtin_amdgcn_s_barrier()
; #define PG8_SCHED __builtin_amdgcn_sched_barrier(0)
; template <class Epi>
; DEV void gemm_phase(LAS unsigned char* lds, const Gemm g, const StaticOrder& S, const Epi& E) {
;     ...
;             PG8_BAR; PG8_WAIT_L(0); PG8_MMA(1, 0, At, B0); PG8_BAR; PG8_SCHED;
;             PG8_STAGE(PG8_SB(0, 1), b2 + hstep, voffB);
;             PG8_WAIT_V(6); PG8_BAR; PG8_MMA(1, 1, At, B1); PG8_BAR;
;             PG8_LDB(B0, 1, 0); PG8_SCHED; PG8_LDA(At, 1, 0); PG8_STAGE(PG8_SA(0, 1), a2 + hstep, voffA);
;             PG8_WAIT_L(8); PG8_BAR; PG8_WAIT_L(0); PG8_MMA(0, 0, At, B0); PG8_BAR; PG8_SCHED;
;             PG8_LDB(B1, 1, 1); PG8_STAGE(PG8_SB(1, 0), b3, voffB);
;             PG8_BAR; PG8_WAIT_L(0); PG8_MMA(0, 1, At, B1); PG8_BAR;
;             PG8_LDA(At, 1, 1); PG8_STAGE(PG8_SA(1, 0), a3, voffA);
;             PG8_BAR; PG8_WAIT_L(0); PG8_MMA(1, 0, At, B0); PG8_BAR; PG8_SCHED;
	s_add_u32 s46, s20, 0x80000
	s_addc_u32 s47, s21, 0
	s_add_i32 s45, s48, s29
	v_lshl_add_u64 v[128:129], s[46:47], 0, v[160:161]
	s_mov_b32 m0, s45
	s_nop 0
	global_load_lds_dwordx4 v[128:129], off
	v_lshl_add_u64 v[128:129], s[46:47], 0, v[136:137]
	s_add_i32 m0, s45, 0x2000
	s_nop 0
	global_load_lds_dwordx4 v[128:129], off
	s_waitcnt vmcnt(6)
	s_barrier
	s_setprio 1
	v_mfma_f32_16x16x32_bf16 v[48:51], v[222:225], v[174:177], v[48:51]
	v_mfma_f32_16x16x32_bf16 v[40:43], v[230:233], v[174:177], v[40:43]
	v_mfma_f32_16x16x32_bf16 v[32:35], v[222:225], v[182:185], v[32:35]
	v_mfma_f32_16x16x32_bf16 v[24:27], v[230:233], v[182:185], v[24:27]
	v_mfma_f32_16x16x32_bf16 v[16:19], v[222:225], v[190:193], v[16:19]
	v_mfma_f32_16x16x32_bf16 v[8:11], v[230:233], v[190:193], v[8:11]
	v_mfma_f32_16x16x32_bf16 v[4:7], v[222:225], v[214:217], v[4:7]
	v_mfma_f32_16x16x32_bf16 v[0:3], v[230:233], v[214:217], v[0:3]
	v_mfma_f32_16x16x32_bf16 v[48:51], v[226:229], v[178:181], v[48:51]
	v_mfma_f32_16x16x32_bf16 v[40:43], v[234:237], v[178:181], v[40:43]
	v_mfma_f32_16x16x32_bf16 v[32:35], v[226:229], v[186:189], v[32:35]
	v_mfma_f32_16x16x32_bf16 v[24:27], v[234:237], v[186:189], v[24:27]
	v_mfma_f32_16x16x32_bf16 v[16:19], v[226:229], v[194:197], v[16:19]
	v_mfma_f32_16x16x32_bf16 v[8:11], v[234:237], v[194:197], v[8:11]
	v_mfma_f32_16x16x32_bf16 v[4:7], v[226:229], v[218:221], v[4:7]
	v_mfma_f32_16x16x32_bf16 v[0:3], v[234:237], v[218:221], v[0:3]
	s_setprio 0
	s_add_i32 s45, 0, 0x18000
	v_add_u32_e32 v146, s45, v149
	s_barrier
	ds_read_b128 v[128:131], v146
	ds_read_b128 v[132:135], v146 offset:1024
	ds_read_b128 v[142:145], v146 offset:2048
	ds_read_b128 v[150:153], v146 offset:3072
	s_add_u32 s22, s22, 0x80000
	s_addc_u32 s23, s23, 0
	s_mov_b32 m0, s34
	v_lshl_add_u64 v[222:223], s[22:23], 0, v[160:161]
	ds_read_b128 v[174:177], v159 offset:32768
	ds_read_b128 v[178:181], v159 offset:33792
	ds_read_b128 v[182:185], v159 offset:34816
	ds_read_b128 v[186:189], v159 offset:35840
	ds_read_b128 v[190:193], v159 offset:36864
	ds_read_b128 v[194:197], v159 offset:37888
	ds_read_b128 v[214:217], v159 offset:38912
	ds_read_b128 v[218:221], v159 offset:39936
	global_load_lds_dwordx4 v[222:223], off
	v_lshl_add_u64 v[222:223], s[22:23], 0, v[136:137]
	s_mov_b32 m0, s35
	s_nop 0
	global_load_lds_dwordx4 v[222:223], off
	s_waitcnt lgkmcnt(8)
	s_barrier
	s_waitcnt lgkmcnt(0)
	s_setprio 1
	s_waitcnt lgkmcnt(0)
	v_mfma_f32_16x16x32_bf16 v[124:127], v[128:131], v[174:177], v[124:127]
	v_mfma_f32_16x16x32_bf16 v[120:123], v[142:145], v[174:177], v[120:123]
	v_mfma_f32_16x16x32_bf16 v[116:119], v[128:131], v[182:185], v[116:119]
	v_mfma_f32_16x16x32_bf16 v[108:111], v[142:145], v[182:185], v[108:111]
	v_mfma_f32_16x16x32_bf16 v[100:103], v[128:131], v[190:193], v[100:103]
	v_mfma_f32_16x16x32_bf16 v[92:95], v[142:145], v[190:193], v[92:95]
	v_mfma_f32_16x16x32_bf16 v[84:87], v[128:131], v[214:217], v[84:87]
	v_mfma_f32_16x16x32_bf16 v[76:79], v[142:145], v[214:217], v[76:79]
	v_mfma_f32_16x16x32_bf16 v[124:127], v[132:135], v[178:181], v[124:127]
	v_mfma_f32_16x16x32_bf16 v[120:123], v[150:153], v[178:181], v[120:123]
	v_mfma_f32_16x16x32_bf16 v[116:119], v[132:135], v[186:189], v[116:119]
	v_mfma_f32_16x16x32_bf16 v[108:111], v[150:153], v[186:189], v[108:111]
	v_mfma_f32_16x16x32_bf16 v[100:103], v[132:135], v[194:197], v[100:103]
	v_mfma_f32_16x16x32_bf16 v[92:95], v[150:153], v[194:197], v[92:95]
	v_mfma_f32_16x16x32_bf16 v[84:87], v[132:135], v[218:221], v[84:87]
	v_mfma_f32_16x16x32_bf16 v[76:79], v[150:153], v[218:221], v[76:79]
	s_setprio 0
	s_barrier
	s_add_i32 s22, 0, 0x1c000
	s_add_i32 s23, s45, s29
	v_add_u32_e32 v146, s22, v149
	v_lshl_add_u64 v[154:155], v[154:155], 0, s[2:3]
	s_mov_b32 m0, s23
	ds_read_b128 v[222:225], v146
	ds_read_b128 v[226:229], v146 offset:1024
	ds_read_b128 v[230:233], v146 offset:2048
	ds_read_b128 v[234:237], v146 offset:3072
	global_load_lds_dwordx4 v[154:155], off
	v_lshl_add_u64 v[154:155], v[238:239], 0, s[2:3]
	s_add_i32 m0, s23, 0x2000
	s_nop 0
	global_load_lds_dwordx4 v[154:155], off
	s_barrier
	s_waitcnt lgkmcnt(0)
	s_setprio 1
	s_waitcnt lgkmcnt(0)
	v_mfma_f32_16x16x32_bf16 v[112:115], v[222:225], v[174:177], v[112:115]
	v_mfma_f32_16x16x32_bf16 v[104:107], v[230:233], v[174:177], v[104:107]
	v_mfma_f32_16x16x32_bf16 v[96:99], v[222:225], v[182:185], v[96:99]
	v_mfma_f32_16x16x32_bf16 v[88:91], v[230:233], v[182:185], v[88:91]
	v_mfma_f32_16x16x32_bf16 v[80:83], v[222:225], v[190:193], v[80:83]
	v_mfma_f32_16x16x32_bf16 v[72:75], v[230:233], v[190:193], v[72:75]
	v_mfma_f32_16x16x32_bf16 v[68:71], v[222:225], v[214:217], v[68:71]
	v_mfma_f32_16x16x32_bf16 v[64:67], v[230:233], v[214:217], v[64:67]
	v_mfma_f32_16x16x32_bf16 v[112:115], v[226:229], v[178:181], v[112:115]
	v_mfma_f32_16x16x32_bf16 v[104:107], v[234:237], v[178:181], v[104:107]
	v_mfma_f32_16x16x32_bf16 v[96:99], v[226:229], v[186:189], v[96:99]
	v_mfma_f32_16x16x32_bf16 v[88:91], v[234:237], v[186:189], v[88:91]
	v_mfma_f32_16x16x32_bf16 v[80:83], v[226:229], v[194:197], v[80:83]
	v_mfma_f32_16x16x32_bf16 v[72:75], v[234:237], v[194:197], v[72:75]
	v_mfma_f32_16x16x32_bf16 v[68:71], v[226:229], v[218:221], v[68:71]
	v_mfma_f32_16x16x32_bf16 v[64:67], v[234:237], v[218:221], v[64:67]
	s_setprio 0
	s_mov_b32 m0, s37
	v_lshl_add_u64 v[154:155], v[240:241], 0, s[2:3]
	s_barrier
	ds_read_b128 v[174:177], v159 offset:49152
	ds_read_b128 v[178:181], v159 offset:50176
	ds_read_b128 v[182:185], v159 offset:51200
	ds_read_b128 v[186:189], v159 offset:52224
	ds_read_b128 v[190:193], v159 offset:53248
	ds_read_b128 v[194:197], v159 offset:54272
	ds_read_b128 v[214:217], v159 offset:55296
	ds_read_b128 v[218:221], v159 offset:56320
	global_load_lds_dwordx4 v[154:155], off
	v_lshl_add_u64 v[154:155], v[242:243], 0, s[2:3]
	s_mov_b32 m0, s38
	s_nop 0
	global_load_lds_dwordx4 v[154:155], off
	s_barrier
; DEV f32x4 gelu4(f32x4 v) { f32x2 a = gelu_pk((f32x2){v[0], v[1]}), b = gelu_pk((f32x2){v[2], v[3]}); return (f32x4){a.x, a.y, b.x, b.y}; }
; #define PG8_STAGE(bufoff, gbase, voff) do { _Pragma("unroll") for (int _i = 0; _i < 2; ++_i) \
;         __builtin_amdgcn_global_load_lds((const unsigned*)((const char*)(gbase) + (voff)[_i]), (LAS unsigned*)(lds + (bufoff) + ldsw + _i * 8192), 16, 0, 0); } while (0)
; #define PG8_MMA(ai, bj, At, Bt) do { __builtin_amdgcn_s_setprio(1); _Pragma("unroll") for (int m = 0; m < 4; ++m) _Pragma("unroll") for (int n = 0; n < 2; ++n) _Pragma("unroll") for (int k = 0; k < 2; ++k) \
;         acc[ai][bj][m][n] = __builtin_amdgcn_mfma_f32_16x16x32_bf16(Bt[n][k], At[m][k], acc[ai][bj][m][n], 0, 0, 0); __builtin_amdgcn_s_setprio(0); } while (0)
; #define PG8_WAIT_V(n) asm volatile("s_waitcnt vmcnt(" #n ")" ::: "memory")
; #define PG8_WAIT_L(n) asm volatile("s_waitcnt lgkmcnt(" #n ")" ::: "memory")
; #define PG8_BAR __builtin_amdgcn_s_barrier()
; #define PG8_SCHED __builtin_amdgcn_sched_barrier(0)
; template <class Epi>
; DEV void gemm_phase(LAS unsigned char* lds, const Gemm g, const StaticOrder& S, const Epi& E) {
;     ...
;             PG8_BAR; PG8_WAIT_L(0); PG8_MMA(1, 0, At, B0); PG8_BAR; PG8_SCHED;
;             PG8_STAGE(PG8_SB(1, 1), b3 + hstep, voffB);
;             PG8_WAIT_V(6); PG8_BAR; PG8_MMA(1, 1, At, B1); PG8_BAR;
; template <int ACT, bool PERM>
; DEV void store_bf16_tile(AccRef acc, u16* O, int ld, int row0, int col0, const float* ss) {
;     ...
;         for (int m = 0; m < 4; ++m) rsv[ai][m] = ss ? rowscale(ss, row0 + ai * 128 + m * 16) : 1.0f;
; #pragma unroll
;     for (int ai = 0; ai < 2; ++ai)
; #pragma unroll
;         for (int m = 0; m < 4; ++m) { u16* rowp = O + (size_t)(row0 + ai * 128 + m * 16) * ld + col0; const float rs = rsv[ai][m];
; #pragma unroll
;             for (int bj = 0; bj < 2; ++bj) { f32x4 v0 = acc[ai][bj][m][0] * rs, v1 = acc[ai][bj][m][1] * rs; if (ACT == 1) { v0 = gelu4(v0); v1 = gelu4(v1); }
	s_waitcnt lgkmcnt(0)
	s_setprio 1
	s_waitcnt lgkmcnt(0)
	v_mfma_f32_16x16x32_bf16 v[60:63], v[128:131], v[174:177], v[60:63]
	v_mfma_f32_16x16x32_bf16 v[56:59], v[142:145], v[174:177], v[56:59]
	v_mfma_f32_16x16x32_bf16 v[52:55], v[128:131], v[182:185], v[52:55]
	v_mfma_f32_16x16x32_bf16 v[44:47], v[142:145], v[182:185], v[44:47]
	v_mfma_f32_16x16x32_bf16 v[36:39], v[128:131], v[190:193], v[36:39]
	v_mfma_f32_16x16x32_bf16 v[28:31], v[142:145], v[190:193], v[28:31]
	v_mfma_f32_16x16x32_bf16 v[20:23], v[128:131], v[214:217], v[20:23]
	v_mfma_f32_16x16x32_bf16 v[12:15], v[142:145], v[214:217], v[12:15]
	v_mfma_f32_16x16x32_bf16 v[60:63], v[132:135], v[178:181], v[60:63]
	v_mfma_f32_16x16x32_bf16 v[56:59], v[150:153], v[178:181], v[56:59]
	v_mfma_f32_16x16x32_bf16 v[52:55], v[132:135], v[186:189], v[52:55]
	v_mfma_f32_16x16x32_bf16 v[44:47], v[150:153], v[186:189], v[44:47]
	v_mfma_f32_16x16x32_bf16 v[36:39], v[132:135], v[194:197], v[36:39]
	v_mfma_f32_16x16x32_bf16 v[28:31], v[150:153], v[194:197], v[28:31]
	v_mfma_f32_16x16x32_bf16 v[20:23], v[132:135], v[218:221], v[20:23]
	v_mfma_f32_16x16x32_bf16 v[12:15], v[150:153], v[218:221], v[12:15]
	s_setprio 0
	s_barrier
	s_add_u32 s20, s20, 0x80080
	s_addc_u32 s21, s21, 0
	s_add_i32 s22, s22, s29
	v_lshl_add_u64 v[128:129], s[20:21], 0, v[160:161]
	s_mov_b32 m0, s22
	s_nop 0
	global_load_lds_dwordx4 v[128:129], off
	v_lshl_add_u64 v[128:129], s[20:21], 0, v[136:137]
	s_add_i32 m0, s22, 0x2000
	s_nop 0
	global_load_lds_dwordx4 v[128:129], off
	s_waitcnt vmcnt(6)
	s_barrier
	s_setprio 1
	v_mfma_f32_16x16x32_bf16 v[48:51], v[222:225], v[174:177], v[48:51]
	v_mfma_f32_16x16x32_bf16 v[40:43], v[230:233], v[174:177], v[40:43]
	v_mfma_f32_16x16x32_bf16 v[32:35], v[222:225], v[182:185], v[32:35]
	v_mfma_f32_16x16x32_bf16 v[24:27], v[230:233], v[182:185], v[24:27]
	v_mfma_f32_16x16x32_bf16 v[16:19], v[222:225], v[190:193], v[16:19]
	v_mfma_f32_16x16x32_bf16 v[8:11], v[230:233], v[190:193], v[8:11]
	v_mfma_f32_16x16x32_bf16 v[4:7], v[222:225], v[214:217], v[4:7]
	v_mfma_f32_16x16x32_bf16 v[0:3], v[230:233], v[214:217], v[0:3]
	v_mfma_f32_16x16x32_bf16 v[48:51], v[226:229], v[178:181], v[48:51]
	v_mfma_f32_16x16x32_bf16 v[40:43], v[234:237], v[178:181], v[40:43]
	v_mfma_f32_16x16x32_bf16 v[32:35], v[226:229], v[186:189], v[32:35]
	v_mfma_f32_16x16x32_bf16 v[24:27], v[234:237], v[186:189], v[24:27]
	v_mfma_f32_16x16x32_bf16 v[16:19], v[226:229], v[194:197], v[16:19]
	v_mfma_f32_16x16x32_bf16 v[8:11], v[234:237], v[194:197], v[8:11]
	v_mfma_f32_16x16x32_bf16 v[4:7], v[226:229], v[218:221], v[4:7]
	v_mfma_f32_16x16x32_bf16 v[0:3], v[234:237], v[218:221], v[0:3]
	s_setprio 0
	s_add_i32 s44, s44, 2
	s_add_u32 s18, s18, 0x100
	s_addc_u32 s19, s19, 0
	s_add_u32 s42, s42, 0x100
	s_addc_u32 s43, s43, 0
	s_cmp_gt_u32 s44, 29
	s_barrier
	s_cbranch_scc0 .LBB0_344
	v_lshl_add_u32 v142, s0, 8, v147
	v_ashrrev_i32_e32 v143, 31, v142
	v_lshlrev_b32_e32 v248, 5, v142
	global_load_dword v255, v248, s[4:5]
	global_load_dword v255, v248, s[4:5] offset:512
	global_load_dword v255, v248, s[4:5] offset:1024
	global_load_dword v255, v248, s[4:5] offset:1536
	v_add_u32_e32 v248, 0x1000, v248
	global_load_dword v255, v248, s[4:5]
	global_load_dword v255, v248, s[4:5] offset:512
	global_load_dword v255, v248, s[4:5] offset:1024
	global_load_dword v255, v248, s[4:5] offset:1536
	v_lshlrev_b64 v[128:129], 5, v[142:143]
	v_lshl_add_u64 v[132:133], s[4:5], 0, v[128:129]
	global_load_dwordx4 v[128:131], v[132:133], off offset:16
	s_nop 0
	global_load_dwordx4 v[132:135], v[132:133], off
	s_mov_b32 s0, 0x3727c5ac
	s_mov_b32 s18, 0x3a000000
	s_mov_b32 s11, 0x800000
	s_mov_b64 s[20:21], s[16:17]
	s_waitcnt vmcnt(0)
	v_mov_b32_e32 v144, v133
	v_mov_b32_e32 v145, v134
	v_mov_b32_e32 v133, v135
	v_pk_add_f32 v[150:151], v[144:145], v[132:133]
	v_or_b32_e32 v144, 16, v142
	v_mov_b32_e32 v132, v130
	v_mov_b32_e32 v133, v128
	v_mov_b32_e32 v128, v131
	v_ashrrev_i32_e32 v145, 31, v144
	v_pk_add_f32 v[152:153], v[132:133], v[128:129]
	v_lshlrev_b64 v[128:129], 5, v[144:145]
	v_lshl_add_u64 v[132:133], s[4:5], 0, v[128:129]
	global_load_dwordx4 v[128:131], v[132:133], off offset:16
	s_nop 0
	global_load_dwordx4 v[132:135], v[132:133], off
	s_waitcnt vmcnt(0)
	v_mov_b32_e32 v154, v133
	v_mov_b32_e32 v155, v134
	v_mov_b32_e32 v133, v135
	v_pk_add_f32 v[132:133], v[154:155], v[132:133]
	v_mov_b32_e32 v134, v130
	v_mov_b32_e32 v135, v128
	v_mov_b32_e32 v128, v131
	v_pk_add_f32 v[128:129], v[134:135], v[128:129]
	v_mov_b32_e32 v130, v132
	v_mov_b32_e32 v131, v150
	v_mov_b32_e32 v150, v133
	v_pk_add_f32 v[130:131], v[130:131], v[150:151]
	v_mov_b32_e32 v132, v129
	v_mov_b32_e32 v133, v153
	v_pk_add_f32 v[130:131], v[130:131], v[132:133]
	v_mov_b32_e32 v129, v152
	v_pk_add_f32 v[128:129], v[128:129], v[130:131]
	v_mov_b64_e32 v[150:151], s[0:1]
	v_pk_fma_f32 v[128:129], v[128:129], s[18:19], v[150:151] op_sel_hi:[1,0,0]
	v_or_b32_e32 v152, 32, v142
	v_mul_f32_e32 v130, 0x4b800000, v129
	v_cmp_gt_f32_e64 s[0:1], s11, v129
	v_cmp_gt_f32_e32 vcc, s11, v128
	v_ashrrev_i32_e32 v153, 31, v152
	v_cndmask_b32_e64 v129, v129, v130, s[0:1]
	v_rsq_f32_e32 v129, v129
	s_nop 0
	v_mul_f32_e32 v130, 0x45800000, v129
	v_cndmask_b32_e64 v148, v129, v130, s[0:1]
	v_mul_f32_e32 v129, 0x4b800000, v128
	v_cndmask_b32_e32 v128, v128, v129, vcc
	v_rsq_f32_e32 v128, v128
	v_pk_mul_f32 v[106:107], v[106:107], v[148:149] op_sel_hi:[1,0]
	v_pk_mul_f32 v[104:105], v[104:105], v[148:149] op_sel_hi:[1,0]
	v_pk_mul_f32 v[114:115], v[114:115], v[148:149] op_sel_hi:[1,0]
	v_mul_f32_e32 v129, 0x45800000, v128
	v_cndmask_b32_e32 v146, v128, v129, vcc
	v_lshlrev_b64 v[128:129], 5, v[152:153]
	v_lshl_add_u64 v[132:133], s[4:5], 0, v[128:129]
	global_load_dwordx4 v[128:131], v[132:133], off offset:16
	s_nop 0
	global_load_dwordx4 v[132:135], v[132:133], off
	v_cvt_pk_bf16_f32 v104, v104, v105
	v_cvt_pk_bf16_f32 v105, v106, v107
	v_pk_mul_f32 v[90:91], v[90:91], v[146:147] op_sel_hi:[1,0]
	v_pk_mul_f32 v[88:89], v[88:89], v[146:147] op_sel_hi:[1,0]
	v_pk_mul_f32 v[112:113], v[112:113], v[148:149] op_sel_hi:[1,0]
	v_cvt_pk_bf16_f32 v88, v88, v89
	v_cvt_pk_bf16_f32 v89, v90, v91
	v_pk_mul_f32 v[98:99], v[98:99], v[146:147] op_sel_hi:[1,0]
	v_pk_mul_f32 v[96:97], v[96:97], v[146:147] op_sel_hi:[1,0]
	v_cvt_pk_bf16_f32 v112, v112, v113
	v_cvt_pk_bf16_f32 v113, v114, v115
	v_cvt_pk_bf16_f32 v96, v96, v97
	v_cvt_pk_bf16_f32 v97, v98, v99
	v_pk_mul_f32 v[126:127], v[126:127], v[148:149] op_sel_hi:[1,0]
	v_pk_mul_f32 v[124:125], v[124:125], v[148:149] op_sel_hi:[1,0]
	v_pk_mul_f32 v[122:123], v[122:123], v[148:149] op_sel_hi:[1,0]
	v_pk_mul_f32 v[120:121], v[120:121], v[148:149] op_sel_hi:[1,0]
	v_pk_mul_f32 v[106:107], v[118:119], v[146:147] op_sel_hi:[1,0]
	v_pk_mul_f32 v[110:111], v[110:111], v[146:147] op_sel_hi:[1,0]
	v_pk_mul_f32 v[108:109], v[108:109], v[146:147] op_sel_hi:[1,0]
	v_cvt_pk_bf16_f32 v124, v124, v125
	v_cvt_pk_bf16_f32 v125, v126, v127
	v_cvt_pk_bf16_f32 v120, v120, v121
	v_cvt_pk_bf16_f32 v121, v122, v123
	s_waitcnt vmcnt(0)
; DEV f32x4 gelu4(f32x4 v) { f32x2 a = gelu_pk((f32x2){v[0], v[1]}), b = gelu_pk((f32x2){v[2], v[3]}); return (f32x4){a.x, a.y, b.x, b.y}; }
; template <int ACT, bool PERM>
; DEV void store_bf16_tile(AccRef acc, u16* O, int ld, int row0, int col0, const float* ss) {
;     ...
;         for (int m = 0; m < 4; ++m) rsv[ai][m] = ss ? rowscale(ss, row0 + ai * 128 + m * 16) : 1.0f;
; #pragma unroll
;     for (int ai = 0; ai < 2; ++ai)
; #pragma unroll
;         for (int m = 0; m < 4; ++m) { u16* rowp = O + (size_t)(row0 + ai * 128 + m * 16) * ld + col0; const float rs = rsv[ai][m];
; #pragma unroll
;             for (int bj = 0; bj < 2; ++bj) { f32x4 v0 = acc[ai][bj][m][0] * rs, v1 = acc[ai][bj][m][1] * rs; if (ACT == 1) { v0 = gelu4(v0); v1 = gelu4(v1); }
	v_mov_b32_e32 v154, v133
	v_mov_b32_e32 v155, v134
	v_mov_b32_e32 v133, v135
	v_pk_add_f32 v[174:175], v[154:155], v[132:133]
	v_or_b32_e32 v154, 48, v142
	v_mov_b32_e32 v132, v130
	v_mov_b32_e32 v133, v128
	v_mov_b32_e32 v128, v131
	v_ashrrev_i32_e32 v155, 31, v154
	v_pk_add_f32 v[176:177], v[132:133], v[128:129]
	v_lshlrev_b64 v[128:129], 5, v[154:155]
	v_lshl_add_u64 v[132:133], s[4:5], 0, v[128:129]
	global_load_dwordx4 v[128:131], v[132:133], off offset:16
	s_nop 0
	global_load_dwordx4 v[132:135], v[132:133], off
	s_waitcnt vmcnt(0)
	v_mov_b32_e32 v178, v133
	v_mov_b32_e32 v179, v134
	v_mov_b32_e32 v133, v135
	v_pk_add_f32 v[132:133], v[178:179], v[132:133]
	v_mov_b32_e32 v134, v130
	v_mov_b32_e32 v135, v128
	v_mov_b32_e32 v128, v131
	v_pk_add_f32 v[128:129], v[134:135], v[128:129]
	v_mov_b32_e32 v130, v132
	v_mov_b32_e32 v131, v174
	v_mov_b32_e32 v174, v133
	v_pk_add_f32 v[130:131], v[130:131], v[174:175]
	v_mov_b32_e32 v132, v129
	v_mov_b32_e32 v133, v177
	v_pk_add_f32 v[130:131], v[130:131], v[132:133]
	v_mov_b32_e32 v129, v176
	v_pk_add_f32 v[128:129], v[128:129], v[130:131]
	v_add_u32_e32 v174, 0x80, v142
	v_pk_fma_f32 v[128:129], v[128:129], s[18:19], v[150:151] op_sel_hi:[1,0,0]
	v_ashrrev_i32_e32 v175, 31, v174
	v_mul_f32_e32 v130, 0x4b800000, v129
	v_cmp_gt_f32_e64 s[0:1], s11, v129
	v_cmp_gt_f32_e32 vcc, s11, v128
	s_nop 0
	v_cndmask_b32_e64 v129, v129, v130, s[0:1]
	v_rsq_f32_e32 v129, v129
	s_nop 0
	v_mul_f32_e32 v130, 0x45800000, v129
	v_cndmask_b32_e64 v158, v129, v130, s[0:1]
	v_mul_f32_e32 v129, 0x4b800000, v128
	v_cndmask_b32_e32 v128, v128, v129, vcc
	v_rsq_f32_e32 v128, v128
	v_pk_mul_f32 v[74:75], v[74:75], v[158:159] op_sel_hi:[1,0]
	v_pk_mul_f32 v[72:73], v[72:73], v[158:159] op_sel_hi:[1,0]
	v_pk_mul_f32 v[82:83], v[82:83], v[158:159] op_sel_hi:[1,0]
	v_mul_f32_e32 v129, 0x45800000, v128
	v_cndmask_b32_e32 v156, v128, v129, vcc
	v_lshlrev_b64 v[128:129], 5, v[174:175]
	v_lshl_add_u64 v[132:133], s[4:5], 0, v[128:129]
	global_load_dwordx4 v[128:131], v[132:133], off offset:16
	s_nop 0
	global_load_dwordx4 v[132:135], v[132:133], off
	v_cvt_pk_bf16_f32 v72, v72, v73
	v_cvt_pk_bf16_f32 v73, v74, v75
	v_pk_mul_f32 v[66:67], v[66:67], v[156:157] op_sel_hi:[1,0]
	v_pk_mul_f32 v[64:65], v[64:65], v[156:157] op_sel_hi:[1,0]
	v_pk_mul_f32 v[80:81], v[80:81], v[158:159] op_sel_hi:[1,0]
	v_cvt_pk_bf16_f32 v64, v64, v65
	v_cvt_pk_bf16_f32 v65, v66, v67
	v_cvt_pk_bf16_f32 v80, v80, v81
	v_cvt_pk_bf16_f32 v81, v82, v83
	v_pk_mul_f32 v[90:91], v[102:103], v[158:159] op_sel_hi:[1,0]
	v_pk_mul_f32 v[94:95], v[94:95], v[158:159] op_sel_hi:[1,0]
	v_pk_mul_f32 v[92:93], v[92:93], v[158:159] op_sel_hi:[1,0]
	v_pk_mul_f32 v[74:75], v[86:87], v[156:157] op_sel_hi:[1,0]
	v_pk_mul_f32 v[78:79], v[78:79], v[156:157] op_sel_hi:[1,0]
	v_pk_mul_f32 v[76:77], v[76:77], v[156:157] op_sel_hi:[1,0]
	v_pk_mul_f32 v[70:71], v[70:71], v[156:157] op_sel_hi:[1,0]
	v_pk_mul_f32 v[68:69], v[68:69], v[156:157] op_sel_hi:[1,0]
	s_waitcnt vmcnt(0)
	v_mov_b32_e32 v176, v133
	v_mov_b32_e32 v177, v134
	v_mov_b32_e32 v133, v135
	v_pk_add_f32 v[178:179], v[176:177], v[132:133]
	v_add_u32_e32 v176, 0x90, v142
	v_mov_b32_e32 v132, v130
	v_mov_b32_e32 v133, v128
	v_mov_b32_e32 v128, v131
	v_ashrrev_i32_e32 v177, 31, v176
	v_pk_add_f32 v[180:181], v[132:133], v[128:129]
	v_lshlrev_b64 v[128:129], 5, v[176:177]
	v_lshl_add_u64 v[132:133], s[4:5], 0, v[128:129]
	global_load_dwordx4 v[128:131], v[132:133], off offset:16
	s_nop 0
	global_load_dwordx4 v[132:135], v[132:133], off
	v_cvt_pk_bf16_f32 v68, v68, v69
	v_cvt_pk_bf16_f32 v69, v70, v71
	s_waitcnt vmcnt(0)
	v_mov_b32_e32 v182, v133
	v_mov_b32_e32 v183, v134
	v_mov_b32_e32 v133, v135
	v_pk_add_f32 v[132:133], v[182:183], v[132:133]
	v_mov_b32_e32 v134, v130
	v_mov_b32_e32 v135, v128
	v_mov_b32_e32 v128, v131
	v_pk_add_f32 v[128:129], v[134:135], v[128:129]
	v_mov_b32_e32 v130, v132
	v_mov_b32_e32 v131, v178
	v_mov_b32_e32 v178, v133
	v_pk_add_f32 v[130:131], v[130:131], v[178:179]
	v_mov_b32_e32 v132, v129
	v_mov_b32_e32 v133, v181
	v_pk_add_f32 v[130:131], v[130:131], v[132:133]
	v_mov_b32_e32 v129, v180
	v_pk_add_f32 v[128:129], v[128:129], v[130:131]
	v_add_u32_e32 v182, 0xa0, v142
	v_pk_fma_f32 v[128:129], v[128:129], s[18:19], v[150:151] op_sel_hi:[1,0,0]
	v_ashrrev_i32_e32 v183, 31, v182
	v_mul_f32_e32 v130, 0x4b800000, v129
	v_cmp_gt_f32_e64 s[0:1], s11, v129
	v_cmp_gt_f32_e32 vcc, s11, v128
	s_nop 0
	v_cndmask_b32_e64 v129, v129, v130, s[0:1]
	v_rsq_f32_e32 v129, v129
	s_nop 0
	v_mul_f32_e32 v130, 0x45800000, v129
	v_cndmask_b32_e64 v180, v129, v130, s[0:1]
	v_mul_f32_e32 v129, 0x4b800000, v128
	v_cndmask_b32_e32 v128, v128, v129, vcc
	v_rsq_f32_e32 v128, v128
	v_pk_mul_f32 v[42:43], v[42:43], v[180:181] op_sel_hi:[1,0]
	v_pk_mul_f32 v[40:41], v[40:41], v[180:181] op_sel_hi:[1,0]
	v_pk_mul_f32 v[50:51], v[50:51], v[180:181] op_sel_hi:[1,0]
	v_mul_f32_e32 v129, 0x45800000, v128
	v_cndmask_b32_e32 v178, v128, v129, vcc
	v_lshlrev_b64 v[128:129], 5, v[182:183]
	v_lshl_add_u64 v[132:133], s[4:5], 0, v[128:129]
	global_load_dwordx4 v[128:131], v[132:133], off offset:16
	s_nop 0
	global_load_dwordx4 v[132:135], v[132:133], off
	v_cvt_pk_bf16_f32 v40, v40, v41
	v_cvt_pk_bf16_f32 v41, v42, v43
	v_pk_mul_f32 v[26:27], v[26:27], v[178:179] op_sel_hi:[1,0]
	v_pk_mul_f32 v[24:25], v[24:25], v[178:179] op_sel_hi:[1,0]
	v_pk_mul_f32 v[48:49], v[48:49], v[180:181] op_sel_hi:[1,0]
	v_cvt_pk_bf16_f32 v24, v24, v25
	v_cvt_pk_bf16_f32 v25, v26, v27
	v_pk_mul_f32 v[34:35], v[34:35], v[178:179] op_sel_hi:[1,0]
	v_pk_mul_f32 v[32:33], v[32:33], v[178:179] op_sel_hi:[1,0]
	v_cvt_pk_bf16_f32 v48, v48, v49
	v_cvt_pk_bf16_f32 v49, v50, v51
	v_cvt_pk_bf16_f32 v32, v32, v33
	v_cvt_pk_bf16_f32 v33, v34, v35
	v_pk_mul_f32 v[62:63], v[62:63], v[180:181] op_sel_hi:[1,0]
	v_pk_mul_f32 v[60:61], v[60:61], v[180:181] op_sel_hi:[1,0]
	v_pk_mul_f32 v[58:59], v[58:59], v[180:181] op_sel_hi:[1,0]
	v_pk_mul_f32 v[56:57], v[56:57], v[180:181] op_sel_hi:[1,0]
	v_pk_mul_f32 v[42:43], v[54:55], v[178:179] op_sel_hi:[1,0]
	v_pk_mul_f32 v[46:47], v[46:47], v[178:179] op_sel_hi:[1,0]
	v_pk_mul_f32 v[44:45], v[44:45], v[178:179] op_sel_hi:[1,0]
	v_cvt_pk_bf16_f32 v60, v60, v61
	v_cvt_pk_bf16_f32 v61, v62, v63
	v_cvt_pk_bf16_f32 v56, v56, v57
	v_cvt_pk_bf16_f32 v57, v58, v59
	s_waitcnt vmcnt(0)
; DEV bf16x8 pack8(f32x4 a, f32x4 b) { u32x4 w; w.x = cvt_pk_bf16(a[0], a[1]); w.y = cvt_pk_bf16(a[2], a[3]); w.z = cvt_pk_bf16(b[0], b[1]); w.w = cvt_pk_bf16(b[2], b[3]); return __builtin_bit_cast(bf16x8, w); }
; DEV u32x2 pack4(f32x4 a) { u32x2 w; w.x = cvt_pk_bf16(a[0], a[1]); w.y = cvt_pk_bf16(a[2], a[3]); return w; }
; DEV f32x4 gelu4(f32x4 v) { f32x2 a = gelu_pk((f32x2){v[0], v[1]}), b = gelu_pk((f32x2){v[2], v[3]}); return (f32x4){a.x, a.y, b.x, b.y}; }
; template <int ACT, bool PERM>
; DEV void store_bf16_tile(AccRef acc, u16* O, int ld, int row0, int col0, const float* ss) {
;     ...
;         for (int m = 0; m < 4; ++m) { u16* rowp = O + (size_t)(row0 + ai * 128 + m * 16) * ld + col0; const float rs = rsv[ai][m];
; #pragma unroll
;             for (int bj = 0; bj < 2; ++bj) { f32x4 v0 = acc[ai][bj][m][0] * rs, v1 = acc[ai][bj][m][1] * rs; if (ACT == 1) { v0 = gelu4(v0); v1 = gelu4(v1); }
;                 if (PERM) *(u32x4*)(rowp + bj * 128) = __builtin_bit_cast(u32x4, pack8(v0, v1));
;                 else { *(u32x2*)(rowp + bj * 128) = pack4(v0); *(u32x2*)(rowp + bj * 128 + 16) = pack4(v1); } } }
	v_mov_b32_e32 v184, v133
	v_mov_b32_e32 v185, v134
	v_mov_b32_e32 v133, v135
	v_pk_add_f32 v[188:189], v[184:185], v[132:133]
	v_add_u32_e32 v184, 0xb0, v142
	v_mov_b32_e32 v132, v130
	v_mov_b32_e32 v133, v128
	v_mov_b32_e32 v128, v131
	v_ashrrev_i32_e32 v185, 31, v184
	v_pk_add_f32 v[186:187], v[132:133], v[128:129]
	v_lshlrev_b64 v[128:129], 5, v[184:185]
	v_lshl_add_u64 v[132:133], s[4:5], 0, v[128:129]
	global_load_dwordx4 v[128:131], v[132:133], off offset:16
	s_nop 0
	global_load_dwordx4 v[132:135], v[132:133], off
	s_waitcnt vmcnt(0)
	v_mov_b32_e32 v190, v133
	v_mov_b32_e32 v191, v134
	v_mov_b32_e32 v133, v135
	v_pk_add_f32 v[132:133], v[190:191], v[132:133]
	v_mov_b32_e32 v134, v130
	v_mov_b32_e32 v135, v128
	v_mov_b32_e32 v128, v131
	v_pk_add_f32 v[128:129], v[134:135], v[128:129]
	v_mov_b32_e32 v130, v132
	v_mov_b32_e32 v131, v188
	v_mov_b32_e32 v188, v133
	v_pk_add_f32 v[130:131], v[130:131], v[188:189]
	v_mov_b32_e32 v132, v129
	v_mov_b32_e32 v133, v187
	v_pk_add_f32 v[130:131], v[130:131], v[132:133]
	v_mov_b32_e32 v129, v186
	v_pk_add_f32 v[128:129], v[128:129], v[130:131]
	v_lshl_or_b32 v132, s40, 8, v157
	v_pk_fma_f32 v[128:129], v[128:129], s[18:19], v[150:151] op_sel_hi:[1,0,0]
	v_ashrrev_i32_e32 v133, 31, v132
	v_mul_f32_e32 v130, 0x4b800000, v129
	v_cmp_gt_f32_e64 s[0:1], s11, v129
	v_lshlrev_b64 v[134:135], 10, v[142:143]
	v_cmp_gt_f32_e32 vcc, s11, v128
	v_cndmask_b32_e64 v129, v129, v130, s[0:1]
	v_rsq_f32_e32 v129, v129
	s_mov_b32 s40, s10
	s_mov_b64 s[18:19], s[14:15]
	v_mul_f32_e32 v130, 0x45800000, v129
	v_cndmask_b32_e64 v130, v129, v130, s[0:1]
	v_readlane_b32 s0, v250, 11
	v_readlane_b32 s1, v250, 12
	v_mul_f32_e32 v129, 0x4b800000, v128
	v_cndmask_b32_e32 v128, v128, v129, vcc
	v_lshl_add_u64 v[132:133], v[132:133], 1, s[0:1]
	v_lshl_add_u64 v[134:135], v[132:133], 0, v[134:135]
	global_store_dwordx2 v[134:135], v[104:105], off offset:288
	v_lshlrev_b64 v[104:105], 10, v[144:145]
	v_lshl_add_u64 v[104:105], v[132:133], 0, v[104:105]
	global_store_dwordx2 v[104:105], v[88:89], off offset:288
	v_lshlrev_b64 v[88:89], 10, v[152:153]
	v_lshl_add_u64 v[88:89], v[132:133], 0, v[88:89]
	global_store_dwordx2 v[88:89], v[72:73], off offset:288
	v_lshlrev_b64 v[72:73], 10, v[154:155]
	v_lshl_add_u64 v[72:73], v[132:133], 0, v[72:73]
	v_rsq_f32_e32 v128, v128
	global_store_dwordx2 v[72:73], v[64:65], off offset:288
	v_lshlrev_b64 v[64:65], 10, v[174:175]
	v_lshl_add_u64 v[64:65], v[132:133], 0, v[64:65]
	global_store_dwordx2 v[64:65], v[40:41], off offset:288
	v_lshlrev_b64 v[40:41], 10, v[176:177]
	v_lshl_add_u64 v[40:41], v[132:133], 0, v[40:41]
	v_mul_f32_e32 v129, 0x45800000, v128
	global_store_dwordx2 v[40:41], v[24:25], off offset:288
	v_lshlrev_b64 v[24:25], 10, v[182:183]
	v_pk_mul_f32 v[18:19], v[18:19], v[130:131] op_sel_hi:[1,0]
	v_pk_mul_f32 v[16:17], v[16:17], v[130:131] op_sel_hi:[1,0]
	v_pk_mul_f32 v[10:11], v[10:11], v[130:131] op_sel_hi:[1,0]
	v_pk_mul_f32 v[8:9], v[8:9], v[130:131] op_sel_hi:[1,0]
	v_cndmask_b32_e32 v128, v128, v129, vcc
	v_lshl_add_u64 v[24:25], v[132:133], 0, v[24:25]
	v_cvt_pk_bf16_f32 v16, v16, v17
	v_cvt_pk_bf16_f32 v17, v18, v19
	v_cvt_pk_bf16_f32 v8, v8, v9
	v_cvt_pk_bf16_f32 v9, v10, v11
	global_store_dwordx2 v[134:135], v[112:113], off offset:256
	v_pk_mul_f32 v[112:113], v[116:117], v[146:147] op_sel_hi:[1,0]
	global_store_dwordx2 v[104:105], v[96:97], off offset:256
	v_pk_mul_f32 v[96:97], v[100:101], v[158:159] op_sel_hi:[1,0]
	global_store_dwordx2 v[88:89], v[80:81], off offset:256
	v_pk_mul_f32 v[80:81], v[84:85], v[156:157] op_sel_hi:[1,0]
	global_store_dwordx2 v[64:65], v[48:49], off offset:256
	v_pk_mul_f32 v[48:49], v[52:53], v[178:179] op_sel_hi:[1,0]
	global_store_dwordx2 v[40:41], v[32:33], off offset:256
	v_pk_mul_f32 v[26:27], v[38:39], v[130:131] op_sel_hi:[1,0]
	v_pk_mul_f32 v[32:33], v[36:37], v[130:131] op_sel_hi:[1,0]
	v_pk_mul_f32 v[30:31], v[30:31], v[130:131] op_sel_hi:[1,0]
	v_pk_mul_f32 v[28:29], v[28:29], v[130:131] op_sel_hi:[1,0]
	global_store_dwordx2 v[24:25], v[16:17], off offset:256
	global_store_dwordx2 v[24:25], v[8:9], off offset:288
	v_lshlrev_b64 v[8:9], 10, v[184:185]
	v_pk_mul_f32 v[10:11], v[22:23], v[128:129] op_sel_hi:[1,0]
	v_pk_mul_f32 v[16:17], v[20:21], v[128:129] op_sel_hi:[1,0]
	v_pk_mul_f32 v[14:15], v[14:15], v[128:129] op_sel_hi:[1,0]
	v_pk_mul_f32 v[12:13], v[12:13], v[128:129] op_sel_hi:[1,0]
	v_pk_mul_f32 v[6:7], v[6:7], v[128:129] op_sel_hi:[1,0]
	v_pk_mul_f32 v[4:5], v[4:5], v[128:129] op_sel_hi:[1,0]
	v_pk_mul_f32 v[2:3], v[2:3], v[128:129] op_sel_hi:[1,0]
	v_pk_mul_f32 v[0:1], v[0:1], v[128:129] op_sel_hi:[1,0]
	v_cvt_pk_bf16_f32 v112, v112, v113
	v_cvt_pk_bf16_f32 v113, v106, v107
	v_cvt_pk_bf16_f32 v106, v108, v109
	v_cvt_pk_bf16_f32 v107, v110, v111
	v_cvt_pk_bf16_f32 v96, v96, v97
	v_cvt_pk_bf16_f32 v97, v90, v91
	v_cvt_pk_bf16_f32 v90, v92, v93
	v_cvt_pk_bf16_f32 v91, v94, v95
	v_cvt_pk_bf16_f32 v80, v80, v81
	v_cvt_pk_bf16_f32 v81, v74, v75
	v_cvt_pk_bf16_f32 v74, v76, v77
	v_cvt_pk_bf16_f32 v75, v78, v79
	v_cvt_pk_bf16_f32 v48, v48, v49
	v_cvt_pk_bf16_f32 v49, v42, v43
	v_cvt_pk_bf16_f32 v42, v44, v45
	v_cvt_pk_bf16_f32 v43, v46, v47
	v_cvt_pk_bf16_f32 v32, v32, v33
	v_cvt_pk_bf16_f32 v33, v26, v27
	v_cvt_pk_bf16_f32 v26, v28, v29
	v_cvt_pk_bf16_f32 v27, v30, v31
	v_lshl_add_u64 v[8:9], v[132:133], 0, v[8:9]
	v_cvt_pk_bf16_f32 v16, v16, v17
	v_cvt_pk_bf16_f32 v17, v10, v11
	v_cvt_pk_bf16_f32 v10, v12, v13
	v_cvt_pk_bf16_f32 v11, v14, v15
	v_cvt_pk_bf16_f32 v4, v4, v5
	v_cvt_pk_bf16_f32 v5, v6, v7
	v_cvt_pk_bf16_f32 v0, v0, v1
	v_cvt_pk_bf16_f32 v1, v2, v3
	s_and_b64 vcc, exec, s[6:7]
	s_mov_b32 s0, s12
	global_store_dwordx2 v[134:135], v[124:125], off
	global_store_dwordx2 v[134:135], v[120:121], off offset:32
	global_store_dwordx2 v[104:105], v[112:113], off
	global_store_dwordx2 v[104:105], v[106:107], off offset:32
	global_store_dwordx2 v[88:89], v[96:97], off
	global_store_dwordx2 v[88:89], v[90:91], off offset:32
	global_store_dwordx2 v[72:73], v[80:81], off
	global_store_dwordx2 v[72:73], v[74:75], off offset:32
	global_store_dwordx2 v[72:73], v[68:69], off offset:256
	global_store_dwordx2 v[64:65], v[60:61], off
	global_store_dwordx2 v[64:65], v[56:57], off offset:32
	global_store_dwordx2 v[40:41], v[48:49], off
	global_store_dwordx2 v[40:41], v[42:43], off offset:32
	global_store_dwordx2 v[24:25], v[32:33], off
	global_store_dwordx2 v[24:25], v[26:27], off offset:32
	global_store_dwordx2 v[8:9], v[16:17], off
	global_store_dwordx2 v[8:9], v[10:11], off offset:32
	global_store_dwordx2 v[8:9], v[4:5], off offset:256
	global_store_dwordx2 v[8:9], v[0:1], off offset:288
	s_cbranch_vccz .LBB0_337
	s_waitcnt vmcnt(0)
	s_cmpk_gt_u32 s25, 0xff
	s_cbranch_scc1 .LBB0_348
	s_barrier

; #define PG8_STAGE(bufoff, gbase, voff) do { _Pragma("unroll") for (int _i = 0; _i < 2; ++_i) \
;         __builtin_amdgcn_global_load_lds((const unsigned*)((const char*)(gbase) + (voff)[_i]), (LAS unsigned*)(lds + (bufoff) + ldsw + _i * 8192), 16, 0, 0); } while (0)
; #define PG8_LDA(dst, b, h) do { _Pragma("unroll") for (int m = 0; m < 4; ++m) _Pragma("unroll") for (int k = 0; k < 2; ++k) dst[m][k] = *(const LAS bf16x8*)(lds + PG8_SA(b, h) + aoff + m * 2048 + k * 1024); } while (0)
; #define PG8_LDB(dst, b, h) do { _Pragma("unroll") for (int n = 0; n < 2; ++n) _Pragma("unroll") for (int k = 0; k < 2; ++k) dst[n][k] = *(const LAS bf16x8*)(lds + PG8_SB(b, h) + boff + n * 2048 + k * 1024); } while (0)
; #define PG8_MMA(ai, bj, At, Bt) do { __builtin_amdgcn_s_setprio(1); _Pragma("unroll") for (int m = 0; m < 4; ++m) _Pragma("unroll") for (int n = 0; n < 2; ++n) _Pragma("unroll") for (int k = 0; k < 2; ++k) \
;         acc[ai][bj][m][n] = __builtin_amdgcn_mfma_f32_16x16x32_bf16(Bt[n][k], At[m][k], acc[ai][bj][m][n], 0, 0, 0); __builtin_amdgcn_s_setprio(0); } while (0)
; #define PG8_WAIT_L(n) asm volatile("s_waitcnt lgkmcnt(" #n ")" ::: "memory")
; #define PG8_BAR __builtin_amdgcn_s_barrier()
; #define PG8_SCHED __builtin_amdgcn_sched_barrier(0)
; template <class Epi>
; DEV void gemm_phase(LAS unsigned char* lds, const Gemm g, const StaticOrder& S, const Epi& E) {
;     ...
;             PG8_LDB(B0, 0, 0); PG8_SCHED; PG8_LDA(At, 0, 0); PG8_STAGE(PG8_SA(1, 1), a1 + hstep, voffA);
;             PG8_WAIT_L(8); PG8_BAR; PG8_WAIT_L(0); PG8_MMA(0, 0, At, B0); PG8_BAR; PG8_SCHED;
;             PG8_LDB(B1, 0, 1); PG8_STAGE(PG8_SB(0, 0), b2, voffB);
;             PG8_BAR; PG8_WAIT_L(0); PG8_MMA(0, 1, At, B1); PG8_BAR;
;             PG8_LDA(At, 0, 1); PG8_STAGE(PG8_SA(0, 0), a2, voffA);
;             PG8_BAR; PG8_WAIT_L(0); PG8_MMA(1, 0, At, B0); PG8_BAR; PG8_SCHED;
.LBB0_588:
	s_add_u32 s16, s14, 0xfff80080
	s_addc_u32 s17, s15, -1
	s_add_i32 s41, 0, 0x10000
	v_add_u32_e32 v154, s41, v167
	ds_read_b128 v[128:131], v154
	ds_read_b128 v[132:135], v154 offset:1024
	ds_read_b128 v[150:153], v154 offset:2048
	ds_read_b128 v[174:177], v154 offset:3072
	s_cmp_eq_u32 s40, 28
	s_cselect_b32 s19, s1, s17
	s_cselect_b32 s18, s9, s16
	s_cselect_b32 s17, s7, s37
	s_cselect_b32 s16, s35, s36
	v_lshl_add_u64 v[154:155], s[14:15], 0, v[146:147]
	s_add_i32 m0, s24, 0xc000
	ds_read_b128 v[182:185], v219
	ds_read_b128 v[190:193], v219 offset:1024
	ds_read_b128 v[194:197], v219 offset:2048
	ds_read_b128 v[220:223], v219 offset:3072
	ds_read_b128 v[224:227], v219 offset:4096
	ds_read_b128 v[228:231], v219 offset:5120
	ds_read_b128 v[232:235], v219 offset:6144
	ds_read_b128 v[236:239], v219 offset:7168
	global_load_lds_dwordx4 v[154:155], off
	v_lshl_add_u64 v[154:155], s[14:15], 0, v[148:149]
	s_add_i32 m0, s24, 0xe000
	s_nop 0
	global_load_lds_dwordx4 v[154:155], off
	s_waitcnt lgkmcnt(8)
	s_barrier
	s_waitcnt lgkmcnt(0)
	s_setprio 1
	s_waitcnt lgkmcnt(0)
	v_mfma_f32_16x16x32_bf16 v[124:127], v[128:131], v[182:185], v[124:127]
	v_mfma_f32_16x16x32_bf16 v[120:123], v[150:153], v[182:185], v[120:123]
	v_mfma_f32_16x16x32_bf16 v[108:111], v[128:131], v[194:197], v[108:111]
	v_mfma_f32_16x16x32_bf16 v[104:107], v[150:153], v[194:197], v[104:107]
	v_mfma_f32_16x16x32_bf16 v[92:95], v[128:131], v[224:227], v[92:95]
	v_mfma_f32_16x16x32_bf16 v[88:91], v[150:153], v[224:227], v[88:91]
	v_mfma_f32_16x16x32_bf16 v[76:79], v[128:131], v[232:235], v[76:79]
	v_mfma_f32_16x16x32_bf16 v[72:75], v[150:153], v[232:235], v[72:75]
	v_mfma_f32_16x16x32_bf16 v[124:127], v[132:135], v[190:193], v[124:127]
	v_mfma_f32_16x16x32_bf16 v[120:123], v[174:177], v[190:193], v[120:123]
	v_mfma_f32_16x16x32_bf16 v[108:111], v[132:135], v[220:223], v[108:111]
	v_mfma_f32_16x16x32_bf16 v[104:107], v[174:177], v[220:223], v[104:107]
	v_mfma_f32_16x16x32_bf16 v[92:95], v[132:135], v[228:231], v[92:95]
	v_mfma_f32_16x16x32_bf16 v[88:91], v[174:177], v[228:231], v[88:91]
	v_mfma_f32_16x16x32_bf16 v[76:79], v[132:135], v[236:239], v[76:79]
	v_mfma_f32_16x16x32_bf16 v[72:75], v[174:177], v[236:239], v[72:75]
	s_setprio 0
	s_barrier
	s_add_i32 s44, 0, 0x14000
	v_add_u32_e32 v154, s44, v167
	s_add_i32 s41, s41, s22
	ds_read_b128 v[240:243], v154
	ds_read_b128 v[244:247], v154 offset:1024
	ds_read_b128 v[186:189], v154 offset:2048
	ds_read_b128 v[214:217], v154 offset:3072
	v_lshl_add_u64 v[154:155], s[16:17], 0, v[140:141]
	s_mov_b32 m0, s41
	v_lshl_add_u64 v[158:159], s[16:17], 0, v[136:137]
	global_load_lds_dwordx4 v[154:155], off
	s_add_i32 m0, s41, 0x2000
	s_nop 0
	global_load_lds_dwordx4 v[158:159], off
	s_barrier
	s_waitcnt lgkmcnt(0)
	s_setprio 1
	s_waitcnt lgkmcnt(0)
	v_mfma_f32_16x16x32_bf16 v[116:119], v[240:243], v[182:185], v[116:119]
	v_mfma_f32_16x16x32_bf16 v[112:115], v[186:189], v[182:185], v[112:115]
	v_mfma_f32_16x16x32_bf16 v[100:103], v[240:243], v[194:197], v[100:103]
	v_mfma_f32_16x16x32_bf16 v[96:99], v[186:189], v[194:197], v[96:99]
	v_mfma_f32_16x16x32_bf16 v[84:87], v[240:243], v[224:227], v[84:87]
	v_mfma_f32_16x16x32_bf16 v[80:83], v[186:189], v[224:227], v[80:83]
	v_mfma_f32_16x16x32_bf16 v[68:71], v[240:243], v[232:235], v[68:71]
	v_mfma_f32_16x16x32_bf16 v[64:67], v[186:189], v[232:235], v[64:67]
	v_mfma_f32_16x16x32_bf16 v[116:119], v[244:247], v[190:193], v[116:119]
	v_mfma_f32_16x16x32_bf16 v[112:115], v[214:217], v[190:193], v[112:115]
	v_mfma_f32_16x16x32_bf16 v[100:103], v[244:247], v[220:223], v[100:103]
	v_mfma_f32_16x16x32_bf16 v[96:99], v[214:217], v[220:223], v[96:99]
	v_mfma_f32_16x16x32_bf16 v[84:87], v[244:247], v[228:231], v[84:87]
	v_mfma_f32_16x16x32_bf16 v[80:83], v[214:217], v[228:231], v[80:83]
	v_mfma_f32_16x16x32_bf16 v[68:71], v[244:247], v[236:239], v[68:71]
	v_mfma_f32_16x16x32_bf16 v[64:67], v[214:217], v[236:239], v[64:67]
	s_setprio 0
	s_mov_b32 m0, s24
	v_lshl_add_u64 v[178:179], s[18:19], 0, v[142:143]
	s_barrier
	ds_read_b128 v[182:185], v219 offset:16384
	ds_read_b128 v[190:193], v219 offset:17408
	ds_read_b128 v[194:197], v219 offset:18432
	ds_read_b128 v[220:223], v219 offset:19456
	ds_read_b128 v[224:227], v219 offset:20480
	ds_read_b128 v[228:231], v219 offset:21504
	ds_read_b128 v[232:235], v219 offset:22528
	ds_read_b128 v[236:239], v219 offset:23552
	global_load_lds_dwordx4 v[178:179], off
	v_lshl_add_u64 v[248:249], s[18:19], 0, v[138:139]
	s_mov_b32 m0, s25
	s_nop 0
	global_load_lds_dwordx4 v[248:249], off
	s_barrier
	s_waitcnt lgkmcnt(0)
	s_setprio 1
	s_waitcnt lgkmcnt(0)
	v_mfma_f32_16x16x32_bf16 v[60:63], v[128:131], v[182:185], v[60:63]
	v_mfma_f32_16x16x32_bf16 v[56:59], v[150:153], v[182:185], v[56:59]
	v_mfma_f32_16x16x32_bf16 v[44:47], v[128:131], v[194:197], v[44:47]
	v_mfma_f32_16x16x32_bf16 v[40:43], v[150:153], v[194:197], v[40:43]
	v_mfma_f32_16x16x32_bf16 v[28:31], v[128:131], v[224:227], v[28:31]
	v_mfma_f32_16x16x32_bf16 v[24:27], v[150:153], v[224:227], v[24:27]
	v_mfma_f32_16x16x32_bf16 v[12:15], v[128:131], v[232:235], v[12:15]
	v_mfma_f32_16x16x32_bf16 v[8:11], v[150:153], v[232:235], v[8:11]
	v_mfma_f32_16x16x32_bf16 v[60:63], v[132:135], v[190:193], v[60:63]
	v_mfma_f32_16x16x32_bf16 v[56:59], v[174:177], v[190:193], v[56:59]
	v_mfma_f32_16x16x32_bf16 v[44:47], v[132:135], v[220:223], v[44:47]
	v_mfma_f32_16x16x32_bf16 v[40:43], v[174:177], v[220:223], v[40:43]
	v_mfma_f32_16x16x32_bf16 v[28:31], v[132:135], v[228:231], v[28:31]
	v_mfma_f32_16x16x32_bf16 v[24:27], v[174:177], v[228:231], v[24:27]
	v_mfma_f32_16x16x32_bf16 v[12:15], v[132:135], v[236:239], v[12:15]
	v_mfma_f32_16x16x32_bf16 v[8:11], v[174:177], v[236:239], v[8:11]
	s_setprio 0
	s_barrier
; #define PG8_STAGE(bufoff, gbase, voff) do { _Pragma("unroll") for (int _i = 0; _i < 2; ++_i) \
;         __builtin_amdgcn_global_load_lds((const unsigned*)((const char*)(gbase) + (voff)[_i]), (LAS unsigned*)(lds + (bufoff) + ldsw + _i * 8192), 16, 0, 0); } while (0)
; #define PG8_LDA(dst, b, h) do { _Pragma("unroll") for (int m = 0; m < 4; ++m) _Pragma("unroll") for (int k = 0; k < 2; ++k) dst[m][k] = *(const LAS bf16x8*)(lds + PG8_SA(b, h) + aoff + m * 2048 + k * 1024); } while (0)
; #define PG8_LDB(dst, b, h) do { _Pragma("unroll") for (int n = 0; n < 2; ++n) _Pragma("unroll") for (int k = 0; k < 2; ++k) dst[n][k] = *(const LAS bf16x8*)(lds + PG8_SB(b, h) + boff + n * 2048 + k * 1024); } while (0)
; #define PG8_MMA(ai, bj, At, Bt) do { __builtin_amdgcn_s_setprio(1); _Pragma("unroll") for (int m = 0; m < 4; ++m) _Pragma("unroll") for (int n = 0; n < 2; ++n) _Pragma("unroll") for (int k = 0; k < 2; ++k) \
;         acc[ai][bj][m][n] = __builtin_amdgcn_mfma_f32_16x16x32_bf16(Bt[n][k], At[m][k], acc[ai][bj][m][n], 0, 0, 0); __builtin_amdgcn_s_setprio(0); } while (0)
; #define PG8_WAIT_V(n) asm volatile("s_waitcnt vmcnt(" #n ")" ::: "memory")
; #define PG8_WAIT_L(n) asm volatile("s_waitcnt lgkmcnt(" #n ")" ::: "memory")
; #define PG8_BAR __builtin_amdgcn_s_barrier()
; #define PG8_SCHED __builtin_amdgcn_sched_barrier(0)
; template <class Epi>
; DEV void gemm_phase(LAS unsigned char* lds, const Gemm g, const StaticOrder& S, const Epi& E) {
;     ...
;             PG8_BAR; PG8_WAIT_L(0); PG8_MMA(1, 0, At, B0); PG8_BAR; PG8_SCHED;
;             PG8_STAGE(PG8_SB(0, 1), b2 + hstep, voffB);
;             PG8_WAIT_V(6); PG8_BAR; PG8_MMA(1, 1, At, B1); PG8_BAR;
;             PG8_LDB(B0, 1, 0); PG8_SCHED; PG8_LDA(At, 1, 0); PG8_STAGE(PG8_SA(0, 1), a2 + hstep, voffA);
;             PG8_WAIT_L(8); PG8_BAR; PG8_WAIT_L(0); PG8_MMA(0, 0, At, B0); PG8_BAR; PG8_SCHED;
;             PG8_LDB(B1, 1, 1); PG8_STAGE(PG8_SB(1, 0), b3, voffB);
;             PG8_BAR; PG8_WAIT_L(0); PG8_MMA(0, 1, At, B1); PG8_BAR;
;             PG8_LDA(At, 1, 1); PG8_STAGE(PG8_SA(1, 0), a3, voffA);
;             PG8_BAR; PG8_WAIT_L(0); PG8_MMA(1, 0, At, B0); PG8_BAR; PG8_SCHED;
	s_add_u32 s42, s16, 0x80000
	s_addc_u32 s43, s17, 0
	s_add_i32 s41, s44, s22
	v_lshl_add_u64 v[128:129], s[42:43], 0, v[140:141]
	s_mov_b32 m0, s41
	s_nop 0
	global_load_lds_dwordx4 v[128:129], off
	v_lshl_add_u64 v[128:129], s[42:43], 0, v[136:137]
	s_add_i32 m0, s41, 0x2000
	s_nop 0
	global_load_lds_dwordx4 v[128:129], off
	s_waitcnt vmcnt(6)
	s_barrier
	s_setprio 1
	v_mfma_f32_16x16x32_bf16 v[52:55], v[240:243], v[182:185], v[52:55]
	v_mfma_f32_16x16x32_bf16 v[48:51], v[186:189], v[182:185], v[48:51]
	v_mfma_f32_16x16x32_bf16 v[36:39], v[240:243], v[194:197], v[36:39]
	v_mfma_f32_16x16x32_bf16 v[32:35], v[186:189], v[194:197], v[32:35]
	v_mfma_f32_16x16x32_bf16 v[20:23], v[240:243], v[224:227], v[20:23]
	v_mfma_f32_16x16x32_bf16 v[16:19], v[186:189], v[224:227], v[16:19]
	v_mfma_f32_16x16x32_bf16 v[4:7], v[240:243], v[232:235], v[4:7]
	v_mfma_f32_16x16x32_bf16 v[0:3], v[186:189], v[232:235], v[0:3]
	v_mfma_f32_16x16x32_bf16 v[52:55], v[244:247], v[190:193], v[52:55]
	v_mfma_f32_16x16x32_bf16 v[48:51], v[214:217], v[190:193], v[48:51]
	v_mfma_f32_16x16x32_bf16 v[36:39], v[244:247], v[220:223], v[36:39]
	v_mfma_f32_16x16x32_bf16 v[32:35], v[214:217], v[220:223], v[32:35]
	v_mfma_f32_16x16x32_bf16 v[20:23], v[244:247], v[228:231], v[20:23]
	v_mfma_f32_16x16x32_bf16 v[16:19], v[214:217], v[228:231], v[16:19]
	v_mfma_f32_16x16x32_bf16 v[4:7], v[244:247], v[236:239], v[4:7]
	v_mfma_f32_16x16x32_bf16 v[0:3], v[214:217], v[236:239], v[0:3]
	s_setprio 0
	s_add_i32 s41, 0, 0x18000
	v_add_u32_e32 v156, s41, v167
	s_barrier
	ds_read_b128 v[128:131], v156
	ds_read_b128 v[132:135], v156 offset:1024
	ds_read_b128 v[150:153], v156 offset:2048
	ds_read_b128 v[174:177], v156 offset:3072
	s_add_u32 s18, s18, 0x80000
	s_addc_u32 s19, s19, 0
	s_mov_b32 m0, s26
	v_lshl_add_u64 v[232:233], s[18:19], 0, v[142:143]
	ds_read_b128 v[182:185], v219 offset:32768
	ds_read_b128 v[186:189], v219 offset:33792
	ds_read_b128 v[190:193], v219 offset:34816
	ds_read_b128 v[194:197], v219 offset:35840
	ds_read_b128 v[214:217], v219 offset:36864
	ds_read_b128 v[220:223], v219 offset:37888
	ds_read_b128 v[224:227], v219 offset:38912
	ds_read_b128 v[228:231], v219 offset:39936
	global_load_lds_dwordx4 v[232:233], off
	v_lshl_add_u64 v[232:233], s[18:19], 0, v[138:139]
	s_mov_b32 m0, s27
	s_nop 0
	global_load_lds_dwordx4 v[232:233], off
	s_waitcnt lgkmcnt(8)
	s_barrier
	s_waitcnt lgkmcnt(0)
	s_setprio 1
	s_waitcnt lgkmcnt(0)
	v_mfma_f32_16x16x32_bf16 v[124:127], v[128:131], v[182:185], v[124:127]
	v_mfma_f32_16x16x32_bf16 v[120:123], v[150:153], v[182:185], v[120:123]
	v_mfma_f32_16x16x32_bf16 v[108:111], v[128:131], v[190:193], v[108:111]
	v_mfma_f32_16x16x32_bf16 v[104:107], v[150:153], v[190:193], v[104:107]
	v_mfma_f32_16x16x32_bf16 v[92:95], v[128:131], v[214:217], v[92:95]
	v_mfma_f32_16x16x32_bf16 v[88:91], v[150:153], v[214:217], v[88:91]
	v_mfma_f32_16x16x32_bf16 v[76:79], v[128:131], v[224:227], v[76:79]
	v_mfma_f32_16x16x32_bf16 v[72:75], v[150:153], v[224:227], v[72:75]
	v_mfma_f32_16x16x32_bf16 v[124:127], v[132:135], v[186:189], v[124:127]
	v_mfma_f32_16x16x32_bf16 v[120:123], v[174:177], v[186:189], v[120:123]
	v_mfma_f32_16x16x32_bf16 v[108:111], v[132:135], v[194:197], v[108:111]
	v_mfma_f32_16x16x32_bf16 v[104:107], v[174:177], v[194:197], v[104:107]
	v_mfma_f32_16x16x32_bf16 v[92:95], v[132:135], v[220:223], v[92:95]
	v_mfma_f32_16x16x32_bf16 v[88:91], v[174:177], v[220:223], v[88:91]
	v_mfma_f32_16x16x32_bf16 v[76:79], v[132:135], v[228:231], v[76:79]
	v_mfma_f32_16x16x32_bf16 v[72:75], v[174:177], v[228:231], v[72:75]
	s_setprio 0
	s_barrier
	s_add_i32 s18, 0, 0x1c000
	s_add_i32 s19, s41, s22
	v_add_u32_e32 v156, s18, v167
	v_lshl_add_u64 v[154:155], v[154:155], 0, s[2:3]
	s_mov_b32 m0, s19
	ds_read_b128 v[232:235], v156
	ds_read_b128 v[236:239], v156 offset:1024
	ds_read_b128 v[240:243], v156 offset:2048
	ds_read_b128 v[244:247], v156 offset:3072
	global_load_lds_dwordx4 v[154:155], off
	v_lshl_add_u64 v[154:155], v[158:159], 0, s[2:3]
	s_add_i32 m0, s19, 0x2000
	s_nop 0
	global_load_lds_dwordx4 v[154:155], off
	s_barrier
	s_waitcnt lgkmcnt(0)
	s_setprio 1
	s_waitcnt lgkmcnt(0)
	v_mfma_f32_16x16x32_bf16 v[116:119], v[232:235], v[182:185], v[116:119]
	v_mfma_f32_16x16x32_bf16 v[112:115], v[240:243], v[182:185], v[112:115]
	v_mfma_f32_16x16x32_bf16 v[100:103], v[232:235], v[190:193], v[100:103]
	v_mfma_f32_16x16x32_bf16 v[96:99], v[240:243], v[190:193], v[96:99]
	v_mfma_f32_16x16x32_bf16 v[84:87], v[232:235], v[214:217], v[84:87]
	v_mfma_f32_16x16x32_bf16 v[80:83], v[240:243], v[214:217], v[80:83]
	v_mfma_f32_16x16x32_bf16 v[68:71], v[232:235], v[224:227], v[68:71]
	v_mfma_f32_16x16x32_bf16 v[64:67], v[240:243], v[224:227], v[64:67]
	v_mfma_f32_16x16x32_bf16 v[116:119], v[236:239], v[186:189], v[116:119]
	v_mfma_f32_16x16x32_bf16 v[112:115], v[244:247], v[186:189], v[112:115]
	v_mfma_f32_16x16x32_bf16 v[100:103], v[236:239], v[194:197], v[100:103]
	v_mfma_f32_16x16x32_bf16 v[96:99], v[244:247], v[194:197], v[96:99]
	v_mfma_f32_16x16x32_bf16 v[84:87], v[236:239], v[220:223], v[84:87]
	v_mfma_f32_16x16x32_bf16 v[80:83], v[244:247], v[220:223], v[80:83]
	v_mfma_f32_16x16x32_bf16 v[68:71], v[236:239], v[228:231], v[68:71]
	v_mfma_f32_16x16x32_bf16 v[64:67], v[244:247], v[228:231], v[64:67]
	s_setprio 0
	s_mov_b32 m0, s28
	v_lshl_add_u64 v[154:155], v[178:179], 0, s[2:3]
	s_barrier
	ds_read_b128 v[182:185], v219 offset:49152
	ds_read_b128 v[186:189], v219 offset:50176
	ds_read_b128 v[190:193], v219 offset:51200
	ds_read_b128 v[194:197], v219 offset:52224
	ds_read_b128 v[214:217], v219 offset:53248
	ds_read_b128 v[220:223], v219 offset:54272
	ds_read_b128 v[224:227], v219 offset:55296
	ds_read_b128 v[228:231], v219 offset:56320
	global_load_lds_dwordx4 v[154:155], off
	v_lshl_add_u64 v[154:155], v[248:249], 0, s[2:3]
	s_mov_b32 m0, s29
	s_nop 0
	global_load_lds_dwordx4 v[154:155], off
	s_barrier
; #define PG8_STAGE(bufoff, gbase, voff) do { _Pragma("unroll") for (int _i = 0; _i < 2; ++_i) \
;         __builtin_amdgcn_global_load_lds((const unsigned*)((const char*)(gbase) + (voff)[_i]), (LAS unsigned*)(lds + (bufoff) + ldsw + _i * 8192), 16, 0, 0); } while (0)
; #define PG8_MMA(ai, bj, At, Bt) do { __builtin_amdgcn_s_setprio(1); _Pragma("unroll") for (int m = 0; m < 4; ++m) _Pragma("unroll") for (int n = 0; n < 2; ++n) _Pragma("unroll") for (int k = 0; k < 2; ++k) \
;         acc[ai][bj][m][n] = __builtin_amdgcn_mfma_f32_16x16x32_bf16(Bt[n][k], At[m][k], acc[ai][bj][m][n], 0, 0, 0); __builtin_amdgcn_s_setprio(0); } while (0)
; #define PG8_WAIT_V(n) asm volatile("s_waitcnt vmcnt(" #n ")" ::: "memory")
; #define PG8_WAIT_L(n) asm volatile("s_waitcnt lgkmcnt(" #n ")" ::: "memory")
; #define PG8_BAR __builtin_amdgcn_s_barrier()
; #define PG8_SCHED __builtin_amdgcn_sched_barrier(0)
; template <class Epi>
; DEV void gemm_phase(LAS unsigned char* lds, const Gemm g, const StaticOrder& S, const Epi& E) {
;     ...
;             PG8_BAR; PG8_WAIT_L(0); PG8_MMA(1, 0, At, B0); PG8_BAR; PG8_SCHED;
;             PG8_STAGE(PG8_SB(1, 1), b3 + hstep, voffB);
;             PG8_WAIT_V(6); PG8_BAR; PG8_MMA(1, 1, At, B1); PG8_BAR;
;     DEV void operator()(AccRef acc, const pg8::Unit& u, int wr, int wc, int fr, int fq) const {
;     ...
;         if (ct < 4096) store_bf16_tile<1, true>(acc, UV, 4096, row0, ct + cw, ss);
;         else if (ct < 6144) store_bf16_tile<0, true>(acc, Z, 2048, row0, ct - 4096 + cw, ss);
;         else if (ct < 9216) store_bf16_tile<0, true>(acc, XBC, 3072, row0, ct - 6144 + cw, ss);
;         else if (wc == 0) {
; #pragma unroll
;             for (int ai = 0; ai < 2; ++ai)
; #pragma unroll
;                 for (int m = 0; m < 4; ++m) { const float rs = rowscale(ss, row0 + ai * 128 + m * 16);
; #pragma unroll
;                     for (int n = 0; n < 2; ++n) *(f32x4*)(DTR + (size_t)(row0 + ai * 128 + m * 16) * 32 + 8 * fq + 4 * n) = acc[ai][0][m][n] * rs; }
	s_waitcnt lgkmcnt(0)
	s_setprio 1
	s_waitcnt lgkmcnt(0)
	v_mfma_f32_16x16x32_bf16 v[60:63], v[128:131], v[182:185], v[60:63]
	v_mfma_f32_16x16x32_bf16 v[56:59], v[150:153], v[182:185], v[56:59]
	v_mfma_f32_16x16x32_bf16 v[44:47], v[128:131], v[190:193], v[44:47]
	v_mfma_f32_16x16x32_bf16 v[40:43], v[150:153], v[190:193], v[40:43]
	v_mfma_f32_16x16x32_bf16 v[28:31], v[128:131], v[214:217], v[28:31]
	v_mfma_f32_16x16x32_bf16 v[24:27], v[150:153], v[214:217], v[24:27]
	v_mfma_f32_16x16x32_bf16 v[12:15], v[128:131], v[224:227], v[12:15]
	v_mfma_f32_16x16x32_bf16 v[8:11], v[150:153], v[224:227], v[8:11]
	v_mfma_f32_16x16x32_bf16 v[60:63], v[132:135], v[186:189], v[60:63]
	v_mfma_f32_16x16x32_bf16 v[56:59], v[174:177], v[186:189], v[56:59]
	v_mfma_f32_16x16x32_bf16 v[44:47], v[132:135], v[194:197], v[44:47]
	v_mfma_f32_16x16x32_bf16 v[40:43], v[174:177], v[194:197], v[40:43]
	v_mfma_f32_16x16x32_bf16 v[28:31], v[132:135], v[220:223], v[28:31]
	v_mfma_f32_16x16x32_bf16 v[24:27], v[174:177], v[220:223], v[24:27]
	v_mfma_f32_16x16x32_bf16 v[12:15], v[132:135], v[228:231], v[12:15]
	v_mfma_f32_16x16x32_bf16 v[8:11], v[174:177], v[228:231], v[8:11]
	s_setprio 0
	s_barrier
	s_add_u32 s16, s16, 0x80080
	s_addc_u32 s17, s17, 0
	s_add_i32 s18, s18, s22
	v_lshl_add_u64 v[128:129], s[16:17], 0, v[140:141]
	s_mov_b32 m0, s18
	s_nop 0
	global_load_lds_dwordx4 v[128:129], off
	v_lshl_add_u64 v[128:129], s[16:17], 0, v[136:137]
	s_add_i32 m0, s18, 0x2000
	s_nop 0
	global_load_lds_dwordx4 v[128:129], off
	s_waitcnt vmcnt(6)
	s_barrier
	s_setprio 1
	v_mfma_f32_16x16x32_bf16 v[52:55], v[232:235], v[182:185], v[52:55]
	v_mfma_f32_16x16x32_bf16 v[48:51], v[240:243], v[182:185], v[48:51]
	v_mfma_f32_16x16x32_bf16 v[36:39], v[232:235], v[190:193], v[36:39]
	v_mfma_f32_16x16x32_bf16 v[32:35], v[240:243], v[190:193], v[32:35]
	v_mfma_f32_16x16x32_bf16 v[20:23], v[232:235], v[214:217], v[20:23]
	v_mfma_f32_16x16x32_bf16 v[16:19], v[240:243], v[214:217], v[16:19]
	v_mfma_f32_16x16x32_bf16 v[4:7], v[232:235], v[224:227], v[4:7]
	v_mfma_f32_16x16x32_bf16 v[0:3], v[240:243], v[224:227], v[0:3]
	v_mfma_f32_16x16x32_bf16 v[52:55], v[236:239], v[186:189], v[52:55]
	v_mfma_f32_16x16x32_bf16 v[48:51], v[244:247], v[186:189], v[48:51]
	v_mfma_f32_16x16x32_bf16 v[36:39], v[236:239], v[194:197], v[36:39]
	v_mfma_f32_16x16x32_bf16 v[32:35], v[244:247], v[194:197], v[32:35]
	v_mfma_f32_16x16x32_bf16 v[20:23], v[236:239], v[220:223], v[20:23]
	v_mfma_f32_16x16x32_bf16 v[16:19], v[244:247], v[220:223], v[16:19]
	v_mfma_f32_16x16x32_bf16 v[4:7], v[236:239], v[228:231], v[4:7]
	v_mfma_f32_16x16x32_bf16 v[0:3], v[244:247], v[228:231], v[0:3]
	s_setprio 0
	s_add_i32 s40, s40, 2
	s_add_u32 s14, s14, 0x100
	s_addc_u32 s15, s15, 0
	s_add_u32 s36, s36, 0x100
	s_addc_u32 s37, s37, 0
	s_cmp_gt_u32 s40, 29
	s_barrier
	s_cbranch_scc0 .LBB0_588
	s_lshl_b32 s7, s34, 8
	v_lshl_add_u32 v150, s0, 8, v157
	v_readlane_b32 s100, v251, 39
	v_readlane_b32 s101, v251, 40
	v_lshlrev_b32_e32 v248, 5, v150
	s_nop 4
	global_load_dword v255, v248, s[100:101]
	global_load_dword v255, v248, s[100:101] offset:512
	global_load_dword v255, v248, s[100:101] offset:1024
	global_load_dword v255, v248, s[100:101] offset:1536
	v_add_u32_e32 v248, 0x1000, v248
	global_load_dword v255, v248, s[100:101]
	global_load_dword v255, v248, s[100:101] offset:512
	global_load_dword v255, v248, s[100:101] offset:1024
	global_load_dword v255, v248, s[100:101] offset:1536
	s_cmp_gt_i32 s34, 15
	s_mov_b64 s[0:1], -1
	s_cbranch_scc0 .LBB0_601
	s_cmp_gt_u32 s34, 23
	s_cbranch_scc0 .LBB0_598
	s_cmp_gt_u32 s34, 35
	s_cbranch_scc0 .LBB0_595
	s_andn2_b64 vcc, exec, s[4:5]
	s_cbranch_vccnz .LBB0_594
	v_ashrrev_i32_e32 v151, 31, v150
	v_readlane_b32 s0, v251, 39
	v_lshlrev_b64 v[128:129], 5, v[150:151]
	v_readlane_b32 s1, v251, 40
	s_mov_b32 s9, 0x800000
	s_nop 0
	v_lshl_add_u64 v[132:133], s[0:1], 0, v[128:129]
	global_load_dwordx4 v[128:131], v[132:133], off offset:16
	s_nop 0
	global_load_dwordx4 v[132:135], v[132:133], off
	s_waitcnt vmcnt(0)
	v_mov_b32_e32 v152, v133
	v_mov_b32_e32 v153, v134
	v_mov_b32_e32 v133, v135
	v_pk_add_f32 v[132:133], v[152:153], v[132:133]
	v_mov_b32_e32 v134, v130
	v_mov_b32_e32 v135, v128
	v_mov_b32_e32 v128, v131
	v_pk_add_f32 v[128:129], v[134:135], v[128:129]
	v_add_f32_e32 v130, v132, v133
	v_add_f32_e32 v129, v130, v129
	v_add_f32_e32 v128, v128, v129
	v_fmamk_f32 v128, v128, 0x3a000000, v199
	v_cmp_gt_f32_e32 vcc, s9, v128
	v_mul_f32_e32 v129, 0x4b800000, v128
	v_lshlrev_b64 v[134:135], 7, v[150:151]
	v_cndmask_b32_e32 v128, v128, v129, vcc
	v_rsq_f32_e32 v128, v128
	v_lshl_add_u64 v[134:135], v[144:145], 0, v[134:135]
	v_or_b32_e32 v152, 16, v150
	v_ashrrev_i32_e32 v153, 31, v152
	v_mul_f32_e32 v129, 0x45800000, v128
	v_cndmask_b32_e32 v132, v128, v129, vcc
	v_pk_mul_f32 v[130:131], v[126:127], v[132:133] op_sel_hi:[1,0]
	v_pk_mul_f32 v[128:129], v[124:125], v[132:133] op_sel_hi:[1,0]
	global_store_dwordx4 v[134:135], v[128:131], off
	s_nop 1
	v_pk_mul_f32 v[130:131], v[122:123], v[132:133] op_sel_hi:[1,0]
	v_pk_mul_f32 v[128:129], v[120:121], v[132:133] op_sel_hi:[1,0]
	global_store_dwordx4 v[134:135], v[128:131], off offset:16
	s_nop 1
	v_lshlrev_b64 v[128:129], 5, v[152:153]
	v_lshl_add_u64 v[132:133], s[0:1], 0, v[128:129]
	global_load_dwordx4 v[128:131], v[132:133], off offset:16
	s_nop 0
	global_load_dwordx4 v[132:135], v[132:133], off
	s_waitcnt vmcnt(0)
;     DEV void operator()(AccRef acc, const pg8::Unit& u, int wr, int wc, int fr, int fq) const {
;     ...
;                 for (int m = 0; m < 4; ++m) { const float rs = rowscale(ss, row0 + ai * 128 + m * 16);
; #pragma unroll
;                     for (int n = 0; n < 2; ++n) *(f32x4*)(DTR + (size_t)(row0 + ai * 128 + m * 16) * 32 + 8 * fq + 4 * n) = acc[ai][0][m][n] * rs; }
	v_mov_b32_e32 v154, v133
	v_mov_b32_e32 v155, v134
	v_mov_b32_e32 v133, v135
	v_pk_add_f32 v[132:133], v[154:155], v[132:133]
	v_mov_b32_e32 v134, v130
	v_mov_b32_e32 v135, v128
	v_mov_b32_e32 v128, v131
	v_pk_add_f32 v[128:129], v[134:135], v[128:129]
	v_add_f32_e32 v130, v132, v133
	v_add_f32_e32 v129, v130, v129
	v_add_f32_e32 v128, v128, v129
	v_fmamk_f32 v128, v128, 0x3a000000, v199
	v_cmp_gt_f32_e32 vcc, s9, v128
	v_mul_f32_e32 v129, 0x4b800000, v128
	v_lshlrev_b64 v[134:135], 7, v[152:153]
	v_cndmask_b32_e32 v128, v128, v129, vcc
	v_rsq_f32_e32 v128, v128
	v_lshl_add_u64 v[134:135], v[144:145], 0, v[134:135]
	v_or_b32_e32 v152, 32, v150
	v_ashrrev_i32_e32 v153, 31, v152
	v_mul_f32_e32 v129, 0x45800000, v128
	v_cndmask_b32_e32 v132, v128, v129, vcc
	v_pk_mul_f32 v[130:131], v[110:111], v[132:133] op_sel_hi:[1,0]
	v_pk_mul_f32 v[128:129], v[108:109], v[132:133] op_sel_hi:[1,0]
	global_store_dwordx4 v[134:135], v[128:131], off
	s_nop 1
	v_pk_mul_f32 v[130:131], v[106:107], v[132:133] op_sel_hi:[1,0]
	v_pk_mul_f32 v[128:129], v[104:105], v[132:133] op_sel_hi:[1,0]
	global_store_dwordx4 v[134:135], v[128:131], off offset:16
	s_nop 1
	v_lshlrev_b64 v[128:129], 5, v[152:153]
	v_lshl_add_u64 v[132:133], s[0:1], 0, v[128:129]
	global_load_dwordx4 v[128:131], v[132:133], off offset:16
	s_nop 0
	global_load_dwordx4 v[132:135], v[132:133], off
	s_waitcnt vmcnt(0)
	v_mov_b32_e32 v154, v133
	v_mov_b32_e32 v155, v134
	v_mov_b32_e32 v133, v135
	v_pk_add_f32 v[132:133], v[154:155], v[132:133]
	v_mov_b32_e32 v134, v130
	v_mov_b32_e32 v135, v128
	v_mov_b32_e32 v128, v131
	v_pk_add_f32 v[128:129], v[134:135], v[128:129]
	v_add_f32_e32 v130, v132, v133
	v_add_f32_e32 v129, v130, v129
	v_add_f32_e32 v128, v128, v129
	v_fmamk_f32 v128, v128, 0x3a000000, v199
	v_cmp_gt_f32_e32 vcc, s9, v128
	v_mul_f32_e32 v129, 0x4b800000, v128
	v_lshlrev_b64 v[134:135], 7, v[152:153]
	v_cndmask_b32_e32 v128, v128, v129, vcc
	v_rsq_f32_e32 v128, v128
	v_lshl_add_u64 v[134:135], v[144:145], 0, v[134:135]
	v_or_b32_e32 v152, 48, v150
	v_ashrrev_i32_e32 v153, 31, v152
	v_mul_f32_e32 v129, 0x45800000, v128
	v_cndmask_b32_e32 v132, v128, v129, vcc
	v_pk_mul_f32 v[130:131], v[94:95], v[132:133] op_sel_hi:[1,0]
	v_pk_mul_f32 v[128:129], v[92:93], v[132:133] op_sel_hi:[1,0]
	global_store_dwordx4 v[134:135], v[128:131], off
	s_nop 1
	v_pk_mul_f32 v[130:131], v[90:91], v[132:133] op_sel_hi:[1,0]
	v_pk_mul_f32 v[128:129], v[88:89], v[132:133] op_sel_hi:[1,0]
	global_store_dwordx4 v[134:135], v[128:131], off offset:16
	s_nop 1
	v_lshlrev_b64 v[128:129], 5, v[152:153]
	v_lshl_add_u64 v[132:133], s[0:1], 0, v[128:129]
	global_load_dwordx4 v[128:131], v[132:133], off offset:16
	s_nop 0
	global_load_dwordx4 v[132:135], v[132:133], off
	s_waitcnt vmcnt(0)
	v_mov_b32_e32 v154, v133
	v_mov_b32_e32 v155, v134
	v_mov_b32_e32 v133, v135
	v_pk_add_f32 v[132:133], v[154:155], v[132:133]
	v_mov_b32_e32 v134, v130
	v_mov_b32_e32 v135, v128
	v_mov_b32_e32 v128, v131
	v_pk_add_f32 v[128:129], v[134:135], v[128:129]
	v_add_f32_e32 v130, v132, v133
	v_add_f32_e32 v129, v130, v129
	v_add_f32_e32 v128, v128, v129
	v_fmamk_f32 v128, v128, 0x3a000000, v199
	v_cmp_gt_f32_e32 vcc, s9, v128
	v_mul_f32_e32 v129, 0x4b800000, v128
	v_lshlrev_b64 v[134:135], 7, v[152:153]
	v_cndmask_b32_e32 v128, v128, v129, vcc
	v_rsq_f32_e32 v128, v128
	v_lshl_add_u64 v[134:135], v[144:145], 0, v[134:135]
	v_add_u32_e32 v152, 0x80, v150
	v_ashrrev_i32_e32 v153, 31, v152
	v_mul_f32_e32 v129, 0x45800000, v128
	v_cndmask_b32_e32 v132, v128, v129, vcc
	v_pk_mul_f32 v[130:131], v[78:79], v[132:133] op_sel_hi:[1,0]
	v_pk_mul_f32 v[128:129], v[76:77], v[132:133] op_sel_hi:[1,0]
	global_store_dwordx4 v[134:135], v[128:131], off
	s_nop 1
	v_pk_mul_f32 v[130:131], v[74:75], v[132:133] op_sel_hi:[1,0]
	v_pk_mul_f32 v[128:129], v[72:73], v[132:133] op_sel_hi:[1,0]
	global_store_dwordx4 v[134:135], v[128:131], off offset:16
	s_nop 1
	v_lshlrev_b64 v[128:129], 5, v[152:153]
	v_lshl_add_u64 v[132:133], s[0:1], 0, v[128:129]
	global_load_dwordx4 v[128:131], v[132:133], off offset:16
	s_nop 0
	global_load_dwordx4 v[132:135], v[132:133], off
	s_waitcnt vmcnt(0)
;     DEV void operator()(AccRef acc, const pg8::Unit& u, int wr, int wc, int fr, int fq) const {
;     ...
;                 for (int m = 0; m < 4; ++m) { const float rs = rowscale(ss, row0 + ai * 128 + m * 16);
; #pragma unroll
;                     for (int n = 0; n < 2; ++n) *(f32x4*)(DTR + (size_t)(row0 + ai * 128 + m * 16) * 32 + 8 * fq + 4 * n) = acc[ai][0][m][n] * rs; }
	v_mov_b32_e32 v154, v133
	v_mov_b32_e32 v155, v134
	v_mov_b32_e32 v133, v135
	v_pk_add_f32 v[132:133], v[154:155], v[132:133]
	v_mov_b32_e32 v134, v130
	v_mov_b32_e32 v135, v128
	v_mov_b32_e32 v128, v131
	v_pk_add_f32 v[128:129], v[134:135], v[128:129]
	v_add_f32_e32 v130, v132, v133
	v_add_f32_e32 v129, v130, v129
	v_add_f32_e32 v128, v128, v129
	v_fmamk_f32 v128, v128, 0x3a000000, v199
	v_cmp_gt_f32_e32 vcc, s9, v128
	v_mul_f32_e32 v129, 0x4b800000, v128
	v_lshlrev_b64 v[134:135], 7, v[152:153]
	v_cndmask_b32_e32 v128, v128, v129, vcc
	v_rsq_f32_e32 v128, v128
	v_lshl_add_u64 v[134:135], v[144:145], 0, v[134:135]
	v_add_u32_e32 v152, 0x90, v150
	v_ashrrev_i32_e32 v153, 31, v152
	v_mul_f32_e32 v129, 0x45800000, v128
	v_cndmask_b32_e32 v132, v128, v129, vcc
	v_pk_mul_f32 v[130:131], v[62:63], v[132:133] op_sel_hi:[1,0]
	v_pk_mul_f32 v[128:129], v[60:61], v[132:133] op_sel_hi:[1,0]
	global_store_dwordx4 v[134:135], v[128:131], off
	s_nop 1
	v_pk_mul_f32 v[130:131], v[58:59], v[132:133] op_sel_hi:[1,0]
	v_pk_mul_f32 v[128:129], v[56:57], v[132:133] op_sel_hi:[1,0]
	global_store_dwordx4 v[134:135], v[128:131], off offset:16
	s_nop 1
	v_lshlrev_b64 v[128:129], 5, v[152:153]
	v_lshl_add_u64 v[132:133], s[0:1], 0, v[128:129]
	global_load_dwordx4 v[128:131], v[132:133], off offset:16
	s_nop 0
	global_load_dwordx4 v[132:135], v[132:133], off
	s_waitcnt vmcnt(0)
	v_mov_b32_e32 v154, v133
	v_mov_b32_e32 v155, v134
	v_mov_b32_e32 v133, v135
	v_pk_add_f32 v[132:133], v[154:155], v[132:133]
	v_mov_b32_e32 v134, v130
	v_mov_b32_e32 v135, v128
	v_mov_b32_e32 v128, v131
	v_pk_add_f32 v[128:129], v[134:135], v[128:129]
	v_add_f32_e32 v130, v132, v133
	v_add_f32_e32 v129, v130, v129
	v_add_f32_e32 v128, v128, v129
	v_fmamk_f32 v128, v128, 0x3a000000, v199
	v_cmp_gt_f32_e32 vcc, s9, v128
	v_mul_f32_e32 v129, 0x4b800000, v128
	v_lshlrev_b64 v[134:135], 7, v[152:153]
	v_cndmask_b32_e32 v128, v128, v129, vcc
	v_rsq_f32_e32 v128, v128
	v_lshl_add_u64 v[134:135], v[144:145], 0, v[134:135]
	v_add_u32_e32 v152, 0xa0, v150
	v_ashrrev_i32_e32 v153, 31, v152
	v_mul_f32_e32 v129, 0x45800000, v128
	v_cndmask_b32_e32 v132, v128, v129, vcc
	v_pk_mul_f32 v[130:131], v[46:47], v[132:133] op_sel_hi:[1,0]
	v_pk_mul_f32 v[128:129], v[44:45], v[132:133] op_sel_hi:[1,0]
	global_store_dwordx4 v[134:135], v[128:131], off
	s_nop 1
	v_pk_mul_f32 v[130:131], v[42:43], v[132:133] op_sel_hi:[1,0]
	v_pk_mul_f32 v[128:129], v[40:41], v[132:133] op_sel_hi:[1,0]
	global_store_dwordx4 v[134:135], v[128:131], off offset:16
	s_nop 1
	v_lshlrev_b64 v[128:129], 5, v[152:153]
	v_lshl_add_u64 v[132:133], s[0:1], 0, v[128:129]
	global_load_dwordx4 v[128:131], v[132:133], off offset:16
	s_nop 0
	global_load_dwordx4 v[132:135], v[132:133], off
	s_waitcnt vmcnt(0)
	v_mov_b32_e32 v154, v133
	v_mov_b32_e32 v155, v134
	v_mov_b32_e32 v133, v135
	v_pk_add_f32 v[132:133], v[154:155], v[132:133]
	v_mov_b32_e32 v134, v130
	v_mov_b32_e32 v135, v128
	v_mov_b32_e32 v128, v131
	v_pk_add_f32 v[128:129], v[134:135], v[128:129]
	v_add_f32_e32 v130, v132, v133
	v_add_f32_e32 v129, v130, v129
	v_add_f32_e32 v128, v128, v129
	v_fmamk_f32 v128, v128, 0x3a000000, v199
	v_cmp_gt_f32_e32 vcc, s9, v128
	v_mul_f32_e32 v129, 0x4b800000, v128
	v_lshlrev_b64 v[134:135], 7, v[152:153]
	v_cndmask_b32_e32 v128, v128, v129, vcc
	v_rsq_f32_e32 v128, v128
	v_lshl_add_u64 v[134:135], v[144:145], 0, v[134:135]
	v_add_u32_e32 v152, 0xb0, v150
	v_ashrrev_i32_e32 v153, 31, v152
	v_mul_f32_e32 v129, 0x45800000, v128
	v_cndmask_b32_e32 v132, v128, v129, vcc
	v_pk_mul_f32 v[130:131], v[30:31], v[132:133] op_sel_hi:[1,0]
	v_pk_mul_f32 v[128:129], v[28:29], v[132:133] op_sel_hi:[1,0]
	global_store_dwordx4 v[134:135], v[128:131], off
	s_nop 1
	v_pk_mul_f32 v[130:131], v[26:27], v[132:133] op_sel_hi:[1,0]
	v_pk_mul_f32 v[128:129], v[24:25], v[132:133] op_sel_hi:[1,0]
	global_store_dwordx4 v[134:135], v[128:131], off offset:16
	s_nop 1
	v_lshlrev_b64 v[128:129], 5, v[152:153]
	v_lshl_add_u64 v[132:133], s[0:1], 0, v[128:129]
	global_load_dwordx4 v[128:131], v[132:133], off offset:16
	s_nop 0
	global_load_dwordx4 v[132:135], v[132:133], off
	s_waitcnt vmcnt(0)
	v_mov_b32_e32 v154, v133
	v_mov_b32_e32 v155, v134
	v_mov_b32_e32 v133, v135
	v_pk_add_f32 v[132:133], v[154:155], v[132:133]
	v_mov_b32_e32 v134, v130
	v_mov_b32_e32 v135, v128
	v_mov_b32_e32 v128, v131
	v_pk_add_f32 v[128:129], v[134:135], v[128:129]
	v_add_f32_e32 v130, v132, v133
	v_add_f32_e32 v129, v130, v129
	v_add_f32_e32 v128, v128, v129
	v_fmamk_f32 v128, v128, 0x3a000000, v199
	v_cmp_gt_f32_e32 vcc, s9, v128
	v_mul_f32_e32 v129, 0x4b800000, v128
	v_lshlrev_b64 v[134:135], 7, v[152:153]
	v_cndmask_b32_e32 v128, v128, v129, vcc
	v_rsq_f32_e32 v128, v128
	v_lshl_add_u64 v[134:135], v[144:145], 0, v[134:135]
	v_mul_f32_e32 v129, 0x45800000, v128
	v_cndmask_b32_e32 v132, v128, v129, vcc
	v_pk_mul_f32 v[130:131], v[14:15], v[132:133] op_sel_hi:[1,0]
	v_pk_mul_f32 v[128:129], v[12:13], v[132:133] op_sel_hi:[1,0]
	global_store_dwordx4 v[134:135], v[128:131], off
	s_nop 1
	v_pk_mul_f32 v[130:131], v[10:11], v[132:133] op_sel_hi:[1,0]
	v_pk_mul_f32 v[128:129], v[8:9], v[132:133] op_sel_hi:[1,0]
	global_store_dwordx4 v[134:135], v[128:131], off offset:16
